# hand-written SWA attention block (window mask folded into the bias LUT) on top of hand-written MLA block with VALU-first Y phase
# speedup vs baseline: 1.0304x; 1.0117x over previous
; #define LAS __attribute__((address_space(3)))
; DI void attn_lut(LAS float* LUT, int tid, const float* relb, int qhead) {
;     if (tid < 259) { const int rel = tid - 129, n = rel < 0 ? -rel : rel; int b;
;         if (n < 8) b = n; else { int m = (31 - __builtin_clz((unsigned)(n * n))) - 6; b = 8 + m; if (b > 15) b = 15; }
;         if (rel > 0) b += 16;
;         LUT[tid] = relb[b * 8 + qhead] * LOG2E; }
; }
; DI void phase_queue(int wv, const Params& p, int l, LAS unsigned char* lds) {
;     ...
;     for (;;) {
;         __syncthreads();
;         if (tid_(wv) == 0) *bc = (int)atomicAdd(ctr, 1u);
;         __syncthreads();
;         int it = *bc;
;         if (it >= N_QITEMS) break;
;         if (it < N_CHAIN) { propagate_chain(wv, p, it, lds); continue; }
;         it -= N_CHAIN;
;         if (it < N_TAIL) {
;             const int seq = it / 12, hh = it % 12, T = seq_len(seq), q0 = T - 16;
;             if (hh < 4) attn_tail<96, false>(wv, lds, QM, 384, hh * 96, KM, 384, hh * 96, VTM + (size_t)hh * 64 * MPAD, seq_start(seq), T, q0, MIX, 1024, 768 + hh * 64, nullptr, 0, 0.f);
;             else { const int head = hh - 4; attn_tail<64, true>(wv, lds, QS, 512, head * 64, KS, 128, (head >> 2) * 64, VTS + (size_t)(head >> 2) * 64 * MPAD, seq_start(seq), T, q0, MIX, 1024, 256 + head * 64,
;                                                                p.in[3], head, fexp2(p.in[23][(size_t)l * 8 + head] * LOG2E)); }
;             continue;
;         }
;         it -= N_TAIL;
;         if (it < N_MLA) {
;             int seq, head, qb;
;             if (it < 256) { seq = 0; head = it & 3; qb = it >> 2; } else { const int m = it - 256; seq = 1 + (m >> 5); head = m & 3; qb = (m >> 2) & 7; }
;             attn_block<96, false>(wv, lds, QM, 384, head * 96, KM, 384, head * 96, VTM + (size_t)head * 64 * MPAD, seq_start(seq), seq_len(seq), qb * 256, MIX, 1024, 768 + head * 64, nullptr, 0, 0.f);
;             continue;
;         }
;         it -= N_MLA;
;         {
;             int seq, head, qb;
;             if (it < 512) { seq = 0; head = it & 7; qb = it >> 3; } else { const int m = it - 512; seq = 1 + (m >> 6); head = m & 7; qb = (m >> 3) & 7; }
;             attn_block<64, true>(wv, lds, QS, 512, head * 64, KS, 128, (head >> 2) * 64, VTS + (size_t)(head >> 2) * 64 * MPAD, seq_start(seq), seq_len(seq), qb * 256, MIX, 1024, 256 + head * 64,
.LBB0_987:
	s_or_b64 exec, exec, s[6:7]
	s_waitcnt lgkmcnt(0)
	s_barrier
	ds_read_b32 v0, v1 offset:57344
	s_movk_i32 s6, 0x1193
	s_waitcnt lgkmcnt(0)
	v_cmp_lt_i32_e32 vcc, s6, v0
	v_readfirstlane_b32 s61, v0
	s_mov_b64 s[6:7], -1
	s_cbranch_vccnz .LBB0_982
	s_cmpk_gt_i32 s61, 0x107
	s_cbranch_scc0 .LBB0_1238
	s_cmpk_gt_u32 s61, 0x293
	s_cbranch_scc0 .LBB0_1171
	s_cmpk_gt_u32 s61, 0x793
	s_cbranch_scc0 .LBB0_1125
	v_writelane_b32 v255, s4, 17
	v_writelane_b32 v255, s5, 18
	v_writelane_b32 v255, s6, 19
	v_writelane_b32 v255, s7, 20
	v_writelane_b32 v255, s8, 21
	v_writelane_b32 v255, s9, 22
	v_writelane_b32 v255, s10, 23
	v_writelane_b32 v255, s11, 24
	v_writelane_b32 v255, s12, 25
	v_writelane_b32 v255, s13, 26
	v_writelane_b32 v255, s14, 27
	v_writelane_b32 v255, s15, 28
	v_writelane_b32 v255, s16, 29
	v_writelane_b32 v255, s17, 30
	v_writelane_b32 v255, s18, 31
	v_writelane_b32 v255, s19, 32
	v_writelane_b32 v255, s20, 33
	v_writelane_b32 v255, s21, 34
	v_writelane_b32 v255, s22, 35
	v_writelane_b32 v255, s23, 36
	v_writelane_b32 v255, s24, 37
	v_writelane_b32 v255, s25, 38
	v_writelane_b32 v255, s26, 39
	v_writelane_b32 v255, s27, 40
	v_writelane_b32 v255, s28, 41
	v_writelane_b32 v255, s29, 42
	v_writelane_b32 v255, s30, 43
	v_writelane_b32 v255, s31, 44
	v_writelane_b32 v255, s36, 45
	v_writelane_b32 v255, s37, 46
	v_writelane_b32 v255, s38, 47
	v_writelane_b32 v255, s39, 48
	v_writelane_b32 v255, s40, 49
	v_writelane_b32 v255, s41, 50
	v_writelane_b32 v255, s42, 51
	v_writelane_b32 v255, s43, 52
	v_writelane_b32 v255, s44, 53
	v_writelane_b32 v255, s45, 54
	v_writelane_b32 v255, s46, 55
	v_writelane_b32 v255, s47, 56
	v_writelane_b32 v255, s48, 57
	v_writelane_b32 v255, s49, 58
	v_writelane_b32 v255, s50, 59
	v_writelane_b32 v255, s51, 60
	s_load_dwordx2 s[40:41], s[0:1], 0x120
	s_load_dwordx2 s[42:43], s[0:1], 0x18
	s_load_dwordx2 s[44:45], s[0:1], 0xb8
	s_sub_u32 s4, s61, 0x794
	s_cmpk_lt_u32 s4, 0x200
	s_cbranch_scc1 .Lswaa_seq0
	s_sub_u32 s5, s4, 0x200
	s_lshr_b32 s9, s5, 6
	s_add_u32 s9, s9, 1
	s_and_b32 s8, s5, 7
	s_bfe_u32 s10, s5, 0x30003
	s_mul_i32 s11, s9, 0x810
	s_add_u32 s11, s11, 0x3800
	s_movk_i32 s13, 33
	s_branch .Lswaa_dec
.Lswaa_seq0:
	s_mov_b32 s9, 0
	s_and_b32 s8, s4, 7
	s_lshr_b32 s10, s4, 3
	s_mov_b32 s11, 0
	s_movk_i32 s13, 0x101
.Lswaa_dec:
	s_lshr_b32 s15, s33, 6
	s_lshl_b32 s4, s10, 2
	s_sub_u32 s5, s4, 2
	s_cmp_eq_u32 s10, 0
	s_cselect_b32 s12, 1, s5
	s_add_u32 s5, s4, 5
	s_sub_u32 s6, s13, 1
	s_min_u32 s5, s5, s6
	s_sub_u32 s5, s5, s12
	s_add_u32 s29, s5, 1
	s_lshl_b32 s49, s10, 8
	s_lshl_b32 s4, s15, 5
	s_add_u32 s49, s49, s4
	s_movk_i32 s50, 0xff7f
	s_movk_i32 s51, 0xff80
	s_waitcnt lgkmcnt(0)
	s_lshl_b32 s4, s8, 2
	s_load_dword s46, s[44:45], s4
	v_add_u32_e32 v21, s33, v254
	v_add_u32_e32 v25, 0xffffff7f, v21
	v_sub_u32_e32 v23, 0, v25
	v_max_i32_e32 v23, v25, v23
	v_mul_u32_u24_e32 v24, v23, v23
	v_ffbh_u32_e32 v24, v24
	v_sub_u32_e32 v24, 33, v24
	v_min_u32_e32 v24, 15, v24
	v_cmp_gt_u32_e32 vcc, 8, v23
	s_nop 1
	v_cndmask_b32_e32 v24, v24, v23, vcc
	v_cmp_lt_i32_e32 vcc, 0, v25
	s_nop 1
	v_cndmask_b32_e64 v23, 0, 16, vcc
	v_add_u32_e32 v24, v24, v23
	v_lshl_add_u32 v24, v24, 3, s8
	v_lshlrev_b32_e32 v24, 2, v24
	v_min_u32_e32 v24, 0x3fc, v24
	global_load_dword v24, v24, s[42:43]
	s_lshl_b32 s4, s8, 7
	s_add_u32 s16, s40, s4
	s_addc_u32 s17, s41, 0
	s_add_u32 s4, s4, 0x200
	s_add_u32 s22, s34, 0x19548000
	s_addc_u32 s23, s35, 0
	s_add_u32 s22, s22, s4
	s_addc_u32 s23, s23, 0
	s_lshr_b32 s5, s8, 2
	s_lshl_b32 s4, s5, 7
	s_lshl_b32 s6, s11, 8
	s_add_u32 s18, s40, 0x50c0000
	s_addc_u32 s19, s41, 0
	s_add_u32 s18, s18, s4
	s_addc_u32 s19, s19, 0
	s_add_u32 s18, s18, s6
	s_addc_u32 s19, s19, 0
	s_mul_i32 s4, s5, 0xa18000
	s_lshl_b32 s6, s11, 1
	s_add_u32 s20, s34, 0x300a8000
	s_addc_u32 s21, s35, 0
	s_add_u32 s20, s20, s4
	s_addc_u32 s21, s21, 0
	s_add_u32 s20, s20, s6
	s_addc_u32 s21, s21, 0
	v_and_b32_e32 v0, 31, v254
	v_lshrrev_b32_e32 v197, 5, v254
	v_mul_u32_u24_e32 v194, 0x90, v0
	v_add_u32_e32 v195, 0x2400, v194
	v_lshl_add_u32 v194, v197, 4, v194
	v_lshl_add_u32 v195, v197, 3, v195
	v_add_u32_e32 v196, 0x1200, v195
	v_add_u32_e32 v198, s49, v0
	v_lshlrev_b32_e32 v20, 2, v197
	v_sub_u32_e32 v20, v20, v198
	v_add_u32_e32 v198, s11, v198
	v_lshlrev_b32_e32 v199, 10, v198
	v_lshl_add_u32 v199, v197, 4, v199
	v_lshlrev_b32_e32 v198, 11, v198
	v_lshl_add_u32 v200, v197, 3, v198
	v_mov_b32_e32 v19, 0x81
	v_mov_b32_e32 v22, 0x80
	s_movk_i32 s48, 0x71c8
	s_mov_b32 s47, 0x28600
	s_movk_i32 s28, 0x80
	s_movk_i32 s27, 0x4000
	s_add_u32 s4, s15, 0
	s_cmpk_gt_u32 s4, 8
	s_cselect_b32 s7, s47, 0x100
	s_cselect_b32 s36, s28, s27
	s_mov_b32 s37, 0
	s_cselect_b32 s42, s20, s18
	s_cselect_b32 s43, s21, s19
	s_cselect_b32 s5, 9, 0
	s_cselect_b32 s6, 0x2400, 0
	s_sub_u32 s4, s4, s5
	s_cmpk_gt_u32 s4, 8
	s_cselect_b32 s5, 9, 0
	s_sub_u32 s4, s4, s5
	s_lshl_b32 s5, s4, 10
	s_add_u32 s24, s5, s6
	s_lshl_b32 s4, s4, 6
	v_add_u32_e32 v197, s4, v254
	v_mul_lo_u32 v198, v197, s48
	v_lshrrev_b32_e32 v198, 18, v198
	v_mul_u32_u24_e32 v186, 9, v198
	v_sub_u32_e32 v197, v197, v186
	v_cmp_ne_u32_e32 vcc, 8, v197
	s_nop 1
	v_cndmask_b32_e32 v197, 0, v197, vcc
	v_mul_lo_u32 v198, v198, s7
	v_lshl_add_u32 v186, v197, 4, v198
	v_mov_b32_e32 v187, 0
	v_lshl_add_u64 v[186:187], s[42:43], 0, v[186:187]
	s_add_u32 s4, s15, 8
	s_cmpk_gt_u32 s4, 8
	s_cselect_b32 s7, s47, 0x100
	s_cselect_b32 s38, s28, s27
	s_mov_b32 s39, 0
	s_cselect_b32 s42, s20, s18
	s_cselect_b32 s43, s21, s19
	s_cselect_b32 s5, 9, 0
	s_cselect_b32 s6, 0x2400, 0
	s_sub_u32 s4, s4, s5
	s_cmpk_gt_u32 s4, 8
	s_cselect_b32 s5, 9, 0
	s_sub_u32 s4, s4, s5
	s_lshl_b32 s5, s4, 10
; #define LAS __attribute__((address_space(3)))
; #define ATT_GLOAD(k0_, k1_, v_, tile) do { const size_t rb = (size_t)base + (size_t)(tile) * 64; \
;         k0_ = *(const u32x4*)(K + (rb + kkey0) * ldk + koff + kpart0 * 8); \
;         if (kc1 < NKC) k1_ = *(const u32x4*)(K + (rb + kkey1) * ldk + koff + kpart1 * 8); \
;         v_ = *(const u32x4*)(Vt + (size_t)vd * MPAD + rb + vpart * 8); } while (0)
; template <int DQK, bool SWA>
; DI void attn_block(int wv, LAS unsigned char* lds, const bf16_t* Q, int ldq, int qoff, const bf16_t* K, int ldk, int koff, const bf16_t* Vt,
;                    int base, int T, int q0, bf16_t* O, int ldo, int ooff, const float* relb, int qhead, float sink_add) {
;     ...
;     const int tid = tid_(wv), lane = tid & 63, w = tid >> 6, r = lane & 31, h = lane >> 5;
;     LAS float* LUT = (LAS float*)(lds + ATT_LUT);
;     __syncthreads();
;     if (SWA) attn_lut(LUT, tid, relb, qhead);
;     const int qw0 = q0 + 32 * w, qpos = qw0 + r; const size_t qrow = (size_t)base + qpos;
;     bf16x8 qf[NKS];
; #pragma unroll
;     for (int ks = 0; ks < NKS; ++ks) qf[ks] = *(const bf16x8*)(Q + qrow * ldq + qoff + 16 * ks + 8 * h);
;     f32x16 o0, o1;
; #pragma unroll
;     for (int i = 0; i < 16; ++i) { o0[i] = 0.f; o1[i] = 0.f; }
;     float lsum = 0.f;
;     const int nt = (T + 63) >> 6;
;     int lo = 0, ntl = nt;
;     if (SWA) { lo = (q0 - 128) >> 6; if (lo < 1) lo = 1; int hi = (q0 + 255 + 128) >> 6; if (hi > nt - 1) hi = nt - 1; ntl = 1 + (hi >= lo ? hi - lo + 1 : 0); }
;     u32x4 kA0, kA1, vA, kB0, kB1, vB;
;     kA1 = (u32x4){0u, 0u, 0u, 0u}; kB1 = kA1;
;     const int kc0 = tid, kc1 = tid + 512;
;     const int kkey0 = kc0 / CPR, kpart0 = kc0 % CPR, kkey1 = kc1 / CPR, kpart1 = kc1 % CPR;
;     const int vd = tid >> 3, vpart = tid & 7;
;     ...
;     ATT_GLOAD(kA0, kA1, vA, ATT_TILE(0)); ATT_LWRITE(kA0, kA1, vA, 0);
;     if (ntl > 1) ATT_GLOAD(kB0, kB1, vB, ATT_TILE(1));
;     if (ntl > 2) ATT_GLOAD(kA0, kA1, vA, ATT_TILE(2));
;     __syncthreads();
;     for (int it = 0; it < ntl; it += 2) {
;         if (it + 1 < ntl) ATT_LWRITE(kB0, kB1, vB, 1);
;         if (it + 3 < ntl) ATT_GLOAD(kB0, kB1, vB, ATT_TILE(it + 3));
	s_add_u32 s25, s5, s6
	s_lshl_b32 s4, s4, 6
	v_add_u32_e32 v197, s4, v254
	v_mul_lo_u32 v198, v197, s48
	v_lshrrev_b32_e32 v198, 18, v198
	v_mul_u32_u24_e32 v188, 9, v198
	v_sub_u32_e32 v197, v197, v188
	v_cmp_ne_u32_e32 vcc, 8, v197
	s_nop 1
	v_cndmask_b32_e32 v197, 0, v197, vcc
	v_mul_lo_u32 v198, v198, s7
	v_lshl_add_u32 v188, v197, 4, v198
	v_mov_b32_e32 v189, 0
	v_lshl_add_u64 v[188:189], s[42:43], 0, v[188:189]
	s_add_u32 s4, s15, 16
	s_cmpk_gt_u32 s4, 8
	s_cselect_b32 s7, s47, 0x100
	s_cselect_b32 s40, s28, s27
	s_mov_b32 s41, 0
	s_cselect_b32 s42, s20, s18
	s_cselect_b32 s43, s21, s19
	s_cselect_b32 s5, 9, 0
	s_cselect_b32 s6, 0x2400, 0
	s_sub_u32 s4, s4, s5
	s_cmpk_gt_u32 s4, 8
	s_cselect_b32 s5, 9, 0
	s_sub_u32 s4, s4, s5
	s_lshl_b32 s5, s4, 10
	s_add_u32 s26, s5, s6
	s_lshl_b32 s4, s4, 6
	v_add_u32_e32 v197, s4, v254
	v_mul_lo_u32 v198, v197, s48
	v_lshrrev_b32_e32 v198, 18, v198
	v_mul_u32_u24_e32 v190, 9, v198
	v_sub_u32_e32 v197, v197, v190
	v_cmp_ne_u32_e32 vcc, 8, v197
	s_nop 1
	v_cndmask_b32_e32 v197, 0, v197, vcc
	v_mul_lo_u32 v198, v198, s7
	v_lshl_add_u32 v190, v197, 4, v198
	v_mov_b32_e32 v191, 0
	v_lshl_add_u64 v[190:191], s[42:43], 0, v[190:191]
	global_load_dwordx4 v[2:5], v199, s[16:17] offset:0
	global_load_dwordx4 v[6:9], v199, s[16:17] offset:32
	global_load_dwordx4 v[10:13], v199, s[16:17] offset:64
	global_load_dwordx4 v[14:17], v199, s[16:17] offset:96
	s_mov_b32 s28, 0x0
	s_add_u32 m0, s28, s24
	s_nop 0
	global_load_lds_dwordx4 v[186:187], off
	s_mul_i32 s4, s36, s12
	s_mov_b32 s5, 0
	v_lshl_add_u64 v[186:187], v[186:187], 0, s[4:5]
	s_add_u32 m0, s28, s25
	s_nop 0
	global_load_lds_dwordx4 v[188:189], off
	s_mul_i32 s4, s38, s12
	s_mov_b32 s5, 0
	v_lshl_add_u64 v[188:189], v[188:189], 0, s[4:5]
	s_add_u32 m0, s28, s26
	s_nop 0
	global_load_lds_dwordx4 v[190:191], off
	s_mul_i32 s4, s40, s12
	s_mov_b32 s5, 0
	v_lshl_add_u64 v[190:191], v[190:191], 0, s[4:5]
	s_mov_b32 s28, 0x4800
	s_add_u32 m0, s28, s24
	s_nop 0
	global_load_lds_dwordx4 v[186:187], off
	v_lshl_add_u64 v[186:187], v[186:187], 0, s[36:37]
	s_add_u32 m0, s28, s25
	s_nop 0
	global_load_lds_dwordx4 v[188:189], off
	v_lshl_add_u64 v[188:189], v[188:189], 0, s[38:39]
	s_add_u32 m0, s28, s26
	s_nop 0
	global_load_lds_dwordx4 v[190:191], off
	v_lshl_add_u64 v[190:191], v[190:191], 0, s[40:41]
	s_mov_b32 s28, 0xf000
	s_add_u32 m0, s28, s24
	s_nop 0
	global_load_lds_dwordx4 v[186:187], off
	v_lshl_add_u64 v[186:187], v[186:187], 0, s[36:37]
	s_add_u32 m0, s28, s25
	s_nop 0
	global_load_lds_dwordx4 v[188:189], off
	v_lshl_add_u64 v[188:189], v[188:189], 0, s[38:39]
	s_add_u32 m0, s28, s26
	s_nop 0
	global_load_lds_dwordx4 v[190:191], off
	v_lshl_add_u64 v[190:191], v[190:191], 0, s[40:41]
	s_mov_b32 s28, 0x13800
	s_add_u32 m0, s28, s24
	s_nop 0
	global_load_lds_dwordx4 v[186:187], off
	v_lshl_add_u64 v[186:187], v[186:187], 0, s[36:37]
	s_add_u32 m0, s28, s25
	s_nop 0
	global_load_lds_dwordx4 v[188:189], off
	v_lshl_add_u64 v[188:189], v[188:189], 0, s[38:39]
	s_add_u32 m0, s28, s26
	s_nop 0
	global_load_lds_dwordx4 v[190:191], off
	v_lshl_add_u64 v[190:191], v[190:191], 0, s[40:41]
	v_mov_b32_e32 v26, 0
	v_mov_b32_e32 v27, 0
	v_mov_b32_e32 v28, 0
	v_mov_b32_e32 v29, 0
	v_mov_b32_e32 v30, 0
	v_mov_b32_e32 v31, 0
	v_mov_b32_e32 v32, 0
	v_mov_b32_e32 v33, 0
	v_mov_b32_e32 v34, 0
	v_mov_b32_e32 v35, 0
	v_mov_b32_e32 v36, 0
	v_mov_b32_e32 v37, 0
	v_mov_b32_e32 v38, 0
	v_mov_b32_e32 v39, 0
	v_mov_b32_e32 v40, 0
	v_mov_b32_e32 v41, 0
	v_mov_b32_e32 v42, 0
	v_mov_b32_e32 v43, 0
	v_mov_b32_e32 v44, 0
	v_mov_b32_e32 v45, 0
	v_mov_b32_e32 v46, 0
	v_mov_b32_e32 v47, 0
	v_mov_b32_e32 v48, 0
	v_mov_b32_e32 v49, 0
	v_mov_b32_e32 v50, 0
	v_mov_b32_e32 v51, 0
	v_mov_b32_e32 v52, 0
	v_mov_b32_e32 v53, 0
	v_mov_b32_e32 v54, 0
	v_mov_b32_e32 v55, 0
	v_mov_b32_e32 v56, 0
	v_mov_b32_e32 v57, 0
	v_mov_b32_e32 v192, 0
	v_mov_b32_e32 v193, 0
	s_waitcnt vmcnt(16)
	v_mul_f32_e32 v24, 0x3fb8aa3b, v24
	v_mov_b32_e32 v23, 0xf149f2ca
	v_cmp_eq_u32_e32 vcc, 0, v21
	s_nop 1
	v_cndmask_b32_e32 v24, v24, v23, vcc
	v_cmp_eq_u32_e32 vcc, 0x102, v21
	s_nop 1
	v_cndmask_b32_e32 v24, v24, v23, vcc
	v_lshlrev_b32_e32 v25, 2, v21
	v_cmp_gt_u32_e32 vcc, 0x103, v21
	s_and_saveexec_b64 s[4:5], vcc
	ds_write_b32 v25, v24 offset:49152
	s_mov_b64 exec, s[4:5]
	s_mov_b32 s14, 0
	s_mov_b32 s30, 0x0
	s_mov_b32 s31, 0x18000
	s_waitcnt vmcnt(9) lgkmcnt(0)
	s_barrier
	s_cmpk_lt_u32 s15, 4
	s_cbranch_scc1 .Lswaa_noskew
	s_barrier
.Lswaa_noskew:
.Lswaa_loop:
	s_add_u32 s4, s12, s14
	s_sub_u32 s4, s4, 1
	s_cmp_eq_u32 s14, 0
	s_cselect_b32 s27, 0, s4
	s_lshl_b32 s4, s27, 6
	s_sub_i32 s5, s4, s49
	s_add_i32 s5, s5, 0x9f
	s_cmp_le_u32 s5, 0x13e
	s_cselect_b32 s42, 1, 0
	s_cmp_lt_u32 s4, 16
	s_cselect_b32 s42, 1, s42
	s_add_u32 s4, s4, 32
	s_sub_i32 s5, s4, s49
	s_add_i32 s5, s5, 0x9f
	s_cmp_le_u32 s5, 0x13e
	s_cselect_b32 s43, 1, 0
	s_cmp_lt_u32 s4, 16
	s_cselect_b32 s43, 1, s43
	s_sub_u32 s5, s13, 1
	s_cmp_eq_u32 s27, s5
	s_cselect_b32 s43, 0, s43
	v_add_u32_e32 v197, s30, v194
	v_add_u32_e32 v198, s30, v195
	v_add_u32_e32 v199, s30, v196
	s_cmp_eq_u32 s42, 0
	s_cbranch_scc1 .Lswaa_xskip0
	ds_read_b128 v[90:93], v197 offset:0
	ds_read_b128 v[94:97], v197 offset:32
	ds_read_b128 v[98:101], v197 offset:64
	ds_read_b128 v[102:105], v197 offset:96
	ds_read_b64 v[138:139], v198 offset:0
	ds_read_b64 v[140:141], v198 offset:16
	ds_read_b64 v[142:143], v199 offset:0
	ds_read_b64 v[144:145], v199 offset:16
	ds_read_b64 v[146:147], v198 offset:32
	ds_read_b64 v[148:149], v198 offset:48
	ds_read_b64 v[150:151], v199 offset:32
	ds_read_b64 v[152:153], v199 offset:48
	s_waitcnt lgkmcnt(11)
	v_mfma_f32_32x32x16_bf16 v[58:73], v[90:93], v[2:5], 0
	s_waitcnt lgkmcnt(10)
	v_mfma_f32_32x32x16_bf16 v[58:73], v[94:97], v[6:9], v[58:73]
	s_waitcnt lgkmcnt(9)
	v_mfma_f32_32x32x16_bf16 v[58:73], v[98:101], v[10:13], v[58:73]
	s_waitcnt lgkmcnt(8)
	v_mfma_f32_32x32x16_bf16 v[58:73], v[102:105], v[14:17], v[58:73]
; DI float fexp2(float x) { return __builtin_amdgcn_exp2f(x); }
; template <int DQK, bool SWA, bool MASK, class KF, class VF>
; DI void attn_subtile(const bf16x8 (&qf)[DQK / 16], f32x16& o0, f32x16& o1, float& lsum, int kbase, int h, int qpos, int T, const LAS float* LUT, KF kfrag, VF vfrag) {
;     ...
;     if (SWA) {
;         float bias[16];
; #pragma unroll
;         for (int i = 0; i < 16; ++i) {
;             const int rel = kbase + (i & 3) + 8 * (i >> 2) + 4 * h - qpos;
;             const int idx = rel < -129 ? -129 : (rel > 129 ? 129 : rel); bias[i] = LUT[idx + 129];
;         }
; #pragma unroll
;         for (int i = 0; i < 16; ++i) {
;             const int kpos = kbase + (i & 3) + 8 * (i >> 2) + 4 * h, rel = kpos - qpos;
;             const float e = fexp2(s[i] + bias[i]);
;             const bool vis = kpos < T && (kpos < 16 || (rel <= 128 && rel >= -128));
;             pv[i] = vis ? e : 0.f; lsum += pv[i];
;         }
.Lswaa_xskip0:
	s_cmp_eq_u32 s43, 0
	s_cbranch_scc1 .Lswaa_xskip1
	ds_read_b128 v[106:109], v197 offset:4608
	ds_read_b128 v[110:113], v197 offset:4640
	ds_read_b128 v[114:117], v197 offset:4672
	ds_read_b128 v[118:121], v197 offset:4704
	ds_read_b64 v[154:155], v198 offset:64
	ds_read_b64 v[156:157], v198 offset:80
	ds_read_b64 v[158:159], v199 offset:64
	ds_read_b64 v[160:161], v199 offset:80
	ds_read_b64 v[162:163], v198 offset:96
	ds_read_b64 v[164:165], v198 offset:112
	ds_read_b64 v[166:167], v199 offset:96
	ds_read_b64 v[168:169], v199 offset:112
	s_waitcnt lgkmcnt(11)
	v_mfma_f32_32x32x16_bf16 v[74:89], v[106:109], v[2:5], 0
	s_waitcnt lgkmcnt(10)
	v_mfma_f32_32x32x16_bf16 v[74:89], v[110:113], v[6:9], v[74:89]
	s_waitcnt lgkmcnt(9)
	v_mfma_f32_32x32x16_bf16 v[74:89], v[114:117], v[10:13], v[74:89]
	s_waitcnt lgkmcnt(8)
	v_mfma_f32_32x32x16_bf16 v[74:89], v[118:121], v[14:17], v[74:89]
.Lswaa_xskip1:
	s_waitcnt vmcnt(6) lgkmcnt(0)
	s_barrier
	s_mov_b32 s28, s31
	s_add_u32 m0, s28, s24
	s_nop 0
	global_load_lds_dwordx4 v[186:187], off
	v_lshl_add_u64 v[186:187], v[186:187], 0, s[36:37]
	s_add_u32 m0, s28, s25
	s_nop 0
	global_load_lds_dwordx4 v[188:189], off
	v_lshl_add_u64 v[188:189], v[188:189], 0, s[38:39]
	s_add_u32 m0, s28, s26
	s_nop 0
	global_load_lds_dwordx4 v[190:191], off
	v_lshl_add_u64 v[190:191], v[190:191], 0, s[40:41]
	s_cmp_eq_u32 s42, 0
	s_cbranch_scc1 .Lswaa_y1
	s_cmp_eq_u32 s27, 0
	s_cbranch_scc1 .Lswaa_y0meta
	s_sub_u32 s5, s13, 1
	s_cmp_eq_u32 s27, s5
	s_cbranch_scc1 .Lswaa_y0last
	s_lshl_b32 s4, s27, 6
	v_add_u32_e32 v18, s4, v20
	v_med3_i32 v122, v18, s50, v19
	v_lshlrev_b32_e32 v122, 2, v122
	ds_read_b32 v122, v122 offset:49668
	v_add_u32_e32 v123, 1, v18
	v_med3_i32 v123, v123, s50, v19
	v_lshlrev_b32_e32 v123, 2, v123
	ds_read_b32 v123, v123 offset:49668
	v_add_u32_e32 v124, 2, v18
	v_med3_i32 v124, v124, s50, v19
	v_lshlrev_b32_e32 v124, 2, v124
	ds_read_b32 v124, v124 offset:49668
	v_add_u32_e32 v125, 3, v18
	v_med3_i32 v125, v125, s50, v19
	v_lshlrev_b32_e32 v125, 2, v125
	ds_read_b32 v125, v125 offset:49668
	v_add_u32_e32 v126, 8, v18
	v_med3_i32 v126, v126, s50, v19
	v_lshlrev_b32_e32 v126, 2, v126
	ds_read_b32 v126, v126 offset:49668
	v_add_u32_e32 v127, 9, v18
	v_med3_i32 v127, v127, s50, v19
	v_lshlrev_b32_e32 v127, 2, v127
	ds_read_b32 v127, v127 offset:49668
	v_add_u32_e32 v128, 10, v18
	v_med3_i32 v128, v128, s50, v19
	v_lshlrev_b32_e32 v128, 2, v128
	ds_read_b32 v128, v128 offset:49668
	v_add_u32_e32 v129, 11, v18
	v_med3_i32 v129, v129, s50, v19
	v_lshlrev_b32_e32 v129, 2, v129
	ds_read_b32 v129, v129 offset:49668
	v_add_u32_e32 v130, 16, v18
	v_med3_i32 v130, v130, s50, v19
	v_lshlrev_b32_e32 v130, 2, v130
	ds_read_b32 v130, v130 offset:49668
	v_add_u32_e32 v131, 17, v18
	v_med3_i32 v131, v131, s50, v19
	v_lshlrev_b32_e32 v131, 2, v131
	ds_read_b32 v131, v131 offset:49668
	v_add_u32_e32 v132, 18, v18
	v_med3_i32 v132, v132, s50, v19
	v_lshlrev_b32_e32 v132, 2, v132
	ds_read_b32 v132, v132 offset:49668
	v_add_u32_e32 v133, 19, v18
	v_med3_i32 v133, v133, s50, v19
	v_lshlrev_b32_e32 v133, 2, v133
	ds_read_b32 v133, v133 offset:49668
	v_add_u32_e32 v134, 24, v18
	v_med3_i32 v134, v134, s50, v19
	v_lshlrev_b32_e32 v134, 2, v134
	ds_read_b32 v134, v134 offset:49668
	v_add_u32_e32 v135, 25, v18
	v_med3_i32 v135, v135, s50, v19
	v_lshlrev_b32_e32 v135, 2, v135
	ds_read_b32 v135, v135 offset:49668
	v_add_u32_e32 v136, 26, v18
	v_med3_i32 v136, v136, s50, v19
	v_lshlrev_b32_e32 v136, 2, v136
	ds_read_b32 v136, v136 offset:49668
	v_add_u32_e32 v137, 27, v18
	v_med3_i32 v137, v137, s50, v19
	v_lshlrev_b32_e32 v137, 2, v137
	ds_read_b32 v137, v137 offset:49668
	s_waitcnt lgkmcnt(0)
	v_add_f32_e32 v58, v58, v122
	v_add_f32_e32 v59, v59, v123
	v_add_f32_e32 v60, v60, v124
	v_add_f32_e32 v61, v61, v125
	v_add_f32_e32 v62, v62, v126
	v_add_f32_e32 v63, v63, v127
	v_add_f32_e32 v64, v64, v128
	v_add_f32_e32 v65, v65, v129
	v_add_f32_e32 v66, v66, v130
	v_add_f32_e32 v67, v67, v131
	v_add_f32_e32 v68, v68, v132
	v_add_f32_e32 v69, v69, v133
	v_add_f32_e32 v70, v70, v134
	v_add_f32_e32 v71, v71, v135
	v_add_f32_e32 v72, v72, v136
	v_add_f32_e32 v73, v73, v137
	v_exp_f32_e32 v58, v58
	v_exp_f32_e32 v59, v59
	v_exp_f32_e32 v60, v60
	v_exp_f32_e32 v61, v61
	v_exp_f32_e32 v62, v62
	v_exp_f32_e32 v63, v63
	v_exp_f32_e32 v64, v64
	v_exp_f32_e32 v65, v65
	v_exp_f32_e32 v66, v66
	v_exp_f32_e32 v67, v67
	v_exp_f32_e32 v68, v68
	v_exp_f32_e32 v69, v69
	v_exp_f32_e32 v70, v70
	v_exp_f32_e32 v71, v71
	v_exp_f32_e32 v72, v72
	v_exp_f32_e32 v73, v73
	v_cvt_pk_bf16_f32 v170, v58, v59
	v_cvt_pk_bf16_f32 v171, v60, v61
	v_cvt_pk_bf16_f32 v172, v62, v63
	v_cvt_pk_bf16_f32 v173, v64, v65
	v_cvt_pk_bf16_f32 v174, v66, v67
	v_cvt_pk_bf16_f32 v175, v68, v69
	v_cvt_pk_bf16_f32 v176, v70, v71
	v_cvt_pk_bf16_f32 v177, v72, v73
	v_add_f32_e32 v192, v192, v58
	v_add_f32_e32 v193, v193, v59
	v_add_f32_e32 v192, v192, v60
	v_add_f32_e32 v193, v193, v61
	v_add_f32_e32 v192, v192, v62
	v_add_f32_e32 v193, v193, v63
	v_add_f32_e32 v192, v192, v64
	v_add_f32_e32 v193, v193, v65
	v_add_f32_e32 v192, v192, v66
	v_add_f32_e32 v193, v193, v67
	v_add_f32_e32 v192, v192, v68
	v_add_f32_e32 v193, v193, v69
	v_add_f32_e32 v192, v192, v70
	v_add_f32_e32 v193, v193, v71
	v_add_f32_e32 v192, v192, v72
	v_add_f32_e32 v193, v193, v73
	s_branch .Lswaa_y1
; DI float fexp2(float x) { return __builtin_amdgcn_exp2f(x); }
; template <int DQK, bool SWA, bool MASK, class KF, class VF>
; DI void attn_subtile(const bf16x8 (&qf)[DQK / 16], f32x16& o0, f32x16& o1, float& lsum, int kbase, int h, int qpos, int T, const LAS float* LUT, KF kfrag, VF vfrag) {
;     ...
;     if (SWA) {
;         float bias[16];
; #pragma unroll
;         for (int i = 0; i < 16; ++i) {
;             const int rel = kbase + (i & 3) + 8 * (i >> 2) + 4 * h - qpos;
;             const int idx = rel < -129 ? -129 : (rel > 129 ? 129 : rel); bias[i] = LUT[idx + 129];
;         }
; #pragma unroll
;         for (int i = 0; i < 16; ++i) {
;             const int kpos = kbase + (i & 3) + 8 * (i >> 2) + 4 * h, rel = kpos - qpos;
;             const float e = fexp2(s[i] + bias[i]);
;             const bool vis = kpos < T && (kpos < 16 || (rel <= 128 && rel >= -128));
;             pv[i] = vis ? e : 0.f; lsum += pv[i];
;         }
.Lswaa_y0meta:
	s_lshl_b32 s4, s27, 6
	v_add_u32_e32 v18, s4, v20
	v_med3_i32 v122, v18, s51, v22
	v_lshlrev_b32_e32 v122, 2, v122
	ds_read_b32 v122, v122 offset:49668
	v_add_u32_e32 v123, 1, v18
	v_med3_i32 v123, v123, s51, v22
	v_lshlrev_b32_e32 v123, 2, v123
	ds_read_b32 v123, v123 offset:49668
	v_add_u32_e32 v124, 2, v18
	v_med3_i32 v124, v124, s51, v22
	v_lshlrev_b32_e32 v124, 2, v124
	ds_read_b32 v124, v124 offset:49668
	v_add_u32_e32 v125, 3, v18
	v_med3_i32 v125, v125, s51, v22
	v_lshlrev_b32_e32 v125, 2, v125
	ds_read_b32 v125, v125 offset:49668
	v_add_u32_e32 v126, 8, v18
	v_med3_i32 v126, v126, s51, v22
	v_lshlrev_b32_e32 v126, 2, v126
	ds_read_b32 v126, v126 offset:49668
	v_add_u32_e32 v127, 9, v18
	v_med3_i32 v127, v127, s51, v22
	v_lshlrev_b32_e32 v127, 2, v127
	ds_read_b32 v127, v127 offset:49668
	v_add_u32_e32 v128, 10, v18
	v_med3_i32 v128, v128, s51, v22
	v_lshlrev_b32_e32 v128, 2, v128
	ds_read_b32 v128, v128 offset:49668
	v_add_u32_e32 v129, 11, v18
	v_med3_i32 v129, v129, s51, v22
	v_lshlrev_b32_e32 v129, 2, v129
	ds_read_b32 v129, v129 offset:49668
	v_add_u32_e32 v130, 16, v18
	v_med3_i32 v130, v130, s50, v19
	v_lshlrev_b32_e32 v130, 2, v130
	ds_read_b32 v130, v130 offset:49668
	v_add_u32_e32 v131, 17, v18
	v_med3_i32 v131, v131, s50, v19
	v_lshlrev_b32_e32 v131, 2, v131
	ds_read_b32 v131, v131 offset:49668
	v_add_u32_e32 v132, 18, v18
	v_med3_i32 v132, v132, s50, v19
	v_lshlrev_b32_e32 v132, 2, v132
	ds_read_b32 v132, v132 offset:49668
	v_add_u32_e32 v133, 19, v18
	v_med3_i32 v133, v133, s50, v19
	v_lshlrev_b32_e32 v133, 2, v133
	ds_read_b32 v133, v133 offset:49668
	v_add_u32_e32 v134, 24, v18
	v_med3_i32 v134, v134, s50, v19
	v_lshlrev_b32_e32 v134, 2, v134
	ds_read_b32 v134, v134 offset:49668
	v_add_u32_e32 v135, 25, v18
	v_med3_i32 v135, v135, s50, v19
	v_lshlrev_b32_e32 v135, 2, v135
	ds_read_b32 v135, v135 offset:49668
	v_add_u32_e32 v136, 26, v18
	v_med3_i32 v136, v136, s50, v19
	v_lshlrev_b32_e32 v136, 2, v136
	ds_read_b32 v136, v136 offset:49668
	v_add_u32_e32 v137, 27, v18
	v_med3_i32 v137, v137, s50, v19
	v_lshlrev_b32_e32 v137, 2, v137
	ds_read_b32 v137, v137 offset:49668
	s_waitcnt lgkmcnt(0)
	v_add_f32_e32 v58, v58, v122
	v_add_f32_e32 v59, v59, v123
	v_add_f32_e32 v60, v60, v124
	v_add_f32_e32 v61, v61, v125
	v_add_f32_e32 v62, v62, v126
	v_add_f32_e32 v63, v63, v127
	v_add_f32_e32 v64, v64, v128
	v_add_f32_e32 v65, v65, v129
	v_add_f32_e32 v66, v66, v130
	v_add_f32_e32 v67, v67, v131
	v_add_f32_e32 v68, v68, v132
	v_add_f32_e32 v69, v69, v133
	v_add_f32_e32 v70, v70, v134
	v_add_f32_e32 v71, v71, v135
	v_add_f32_e32 v72, v72, v136
	v_add_f32_e32 v73, v73, v137
	v_exp_f32_e32 v58, v58
	v_exp_f32_e32 v59, v59
	v_exp_f32_e32 v60, v60
	v_exp_f32_e32 v61, v61
	v_exp_f32_e32 v62, v62
	v_exp_f32_e32 v63, v63
	v_exp_f32_e32 v64, v64
	v_exp_f32_e32 v65, v65
	v_exp_f32_e32 v66, v66
	v_exp_f32_e32 v67, v67
	v_exp_f32_e32 v68, v68
	v_exp_f32_e32 v69, v69
	v_exp_f32_e32 v70, v70
	v_exp_f32_e32 v71, v71
	v_exp_f32_e32 v72, v72
	v_exp_f32_e32 v73, v73
	v_cvt_pk_bf16_f32 v170, v58, v59
	v_cvt_pk_bf16_f32 v171, v60, v61
	v_cvt_pk_bf16_f32 v172, v62, v63
	v_cvt_pk_bf16_f32 v173, v64, v65
	v_cvt_pk_bf16_f32 v174, v66, v67
	v_cvt_pk_bf16_f32 v175, v68, v69
	v_cvt_pk_bf16_f32 v176, v70, v71
	v_cvt_pk_bf16_f32 v177, v72, v73
	v_add_f32_e32 v192, v192, v58
	v_add_f32_e32 v193, v193, v59
	v_add_f32_e32 v192, v192, v60
	v_add_f32_e32 v193, v193, v61
	v_add_f32_e32 v192, v192, v62
	v_add_f32_e32 v193, v193, v63
	v_add_f32_e32 v192, v192, v64
	v_add_f32_e32 v193, v193, v65
	v_add_f32_e32 v192, v192, v66
	v_add_f32_e32 v193, v193, v67
	v_add_f32_e32 v192, v192, v68
	v_add_f32_e32 v193, v193, v69
	v_add_f32_e32 v192, v192, v70
	v_add_f32_e32 v193, v193, v71
	v_add_f32_e32 v192, v192, v72
	v_add_f32_e32 v193, v193, v73
	s_branch .Lswaa_y1
.Lswaa_y0last:
	s_lshl_b32 s4, s27, 6
	v_add_u32_e32 v18, s4, v20
	v_med3_i32 v122, v18, s50, v19
	v_lshlrev_b32_e32 v122, 2, v122
	ds_read_b32 v122, v122 offset:49668
	v_add_u32_e32 v123, 1, v18
	v_med3_i32 v123, v123, s50, v19
	v_lshlrev_b32_e32 v123, 2, v123
	ds_read_b32 v123, v123 offset:49668
	v_add_u32_e32 v124, 2, v18
	v_med3_i32 v124, v124, s50, v19
	v_lshlrev_b32_e32 v124, 2, v124
	ds_read_b32 v124, v124 offset:49668
	v_add_u32_e32 v125, 3, v18
	v_med3_i32 v125, v125, s50, v19
	v_lshlrev_b32_e32 v125, 2, v125
	ds_read_b32 v125, v125 offset:49668
	v_add_u32_e32 v126, 8, v18
	v_med3_i32 v126, v126, s50, v19
	v_lshlrev_b32_e32 v126, 2, v126
	ds_read_b32 v126, v126 offset:49668
	v_add_u32_e32 v127, 9, v18
	v_med3_i32 v127, v127, s50, v19
	v_lshlrev_b32_e32 v127, 2, v127
	ds_read_b32 v127, v127 offset:49668
	v_add_u32_e32 v128, 10, v18
	v_med3_i32 v128, v128, s50, v19
	v_lshlrev_b32_e32 v128, 2, v128
	ds_read_b32 v128, v128 offset:49668
	v_add_u32_e32 v129, 11, v18
	v_med3_i32 v129, v129, s50, v19
	v_lshlrev_b32_e32 v129, 2, v129
	ds_read_b32 v129, v129 offset:49668
	s_waitcnt lgkmcnt(0)
	v_add_f32_e32 v58, v58, v122
	v_add_f32_e32 v59, v59, v123
	v_add_f32_e32 v60, v60, v124
	v_add_f32_e32 v61, v61, v125
	v_add_f32_e32 v62, v62, v126
	v_add_f32_e32 v63, v63, v127
	v_add_f32_e32 v64, v64, v128
	v_add_f32_e32 v65, v65, v129
	v_mov_b32_e32 v66, 0
	v_mov_b32_e32 v67, 0
	v_mov_b32_e32 v68, 0
	v_mov_b32_e32 v69, 0
	v_mov_b32_e32 v70, 0
	v_mov_b32_e32 v71, 0
	v_mov_b32_e32 v72, 0
	v_mov_b32_e32 v73, 0
	v_exp_f32_e32 v58, v58
	v_exp_f32_e32 v59, v59
	v_exp_f32_e32 v60, v60
	v_exp_f32_e32 v61, v61
	v_exp_f32_e32 v62, v62
	v_exp_f32_e32 v63, v63
	v_exp_f32_e32 v64, v64
	v_exp_f32_e32 v65, v65
	v_cvt_pk_bf16_f32 v170, v58, v59
	v_cvt_pk_bf16_f32 v171, v60, v61
	v_cvt_pk_bf16_f32 v172, v62, v63
	v_cvt_pk_bf16_f32 v173, v64, v65
	v_cvt_pk_bf16_f32 v174, v66, v67
	v_cvt_pk_bf16_f32 v175, v68, v69
	v_cvt_pk_bf16_f32 v176, v70, v71
	v_cvt_pk_bf16_f32 v177, v72, v73
	v_add_f32_e32 v192, v192, v58
	v_add_f32_e32 v193, v193, v59
	v_add_f32_e32 v192, v192, v60
	v_add_f32_e32 v193, v193, v61
	v_add_f32_e32 v192, v192, v62
	v_add_f32_e32 v193, v193, v63
	v_add_f32_e32 v192, v192, v64
	v_add_f32_e32 v193, v193, v65
	v_add_f32_e32 v192, v192, v66
	v_add_f32_e32 v193, v193, v67
	v_add_f32_e32 v192, v192, v68
	v_add_f32_e32 v193, v193, v69
	v_add_f32_e32 v192, v192, v70
	v_add_f32_e32 v193, v193, v71
	v_add_f32_e32 v192, v192, v72
	v_add_f32_e32 v193, v193, v73
; DI unsigned pack2(float lo, float hi) { f32x2 v = {lo, hi}; bf16v2 r = __builtin_convertvector(v, bf16v2); return __builtin_bit_cast(unsigned, r); }
; DI float fexp2(float x) { return __builtin_amdgcn_exp2f(x); }
; #define MFMA32(a, b, c) __builtin_amdgcn_mfma_f32_32x32x16_bf16((a), (b), (c), 0, 0, 0)
; template <int DQK, bool SWA, bool MASK, class KF, class VF>
; DI void attn_subtile(const bf16x8 (&qf)[DQK / 16], f32x16& o0, f32x16& o1, float& lsum, int kbase, int h, int qpos, int T, const LAS float* LUT, KF kfrag, VF vfrag) {
;     ...
;     if (SWA) {
;         float bias[16];
; #pragma unroll
;         for (int i = 0; i < 16; ++i) {
;             const int rel = kbase + (i & 3) + 8 * (i >> 2) + 4 * h - qpos;
;             const int idx = rel < -129 ? -129 : (rel > 129 ? 129 : rel); bias[i] = LUT[idx + 129];
;         }
; #pragma unroll
;         for (int i = 0; i < 16; ++i) {
;             const int kpos = kbase + (i & 3) + 8 * (i >> 2) + 4 * h, rel = kpos - qpos;
;             const float e = fexp2(s[i] + bias[i]);
;             const bool vis = kpos < T && (kpos < 16 || (rel <= 128 && rel >= -128));
;             pv[i] = vis ? e : 0.f; lsum += pv[i];
;         }
;     } else {
; #pragma unroll
;         for (int i = 0; i < 16; ++i) {
;             const float e = fexp2(s[i]);
;             if (MASK) { const int kpos = kbase + (i & 3) + 8 * (i >> 2) + 4 * h; pv[i] = kpos < T ? e : 0.f; } else pv[i] = e;
;             lsum += pv[i];
;         }
;     }
; #pragma unroll
;     for (int s2 = 0; s2 < 2; ++s2) {
;         u32x4 pk = {pack2(pv[8 * s2], pv[8 * s2 + 1]), pack2(pv[8 * s2 + 2], pv[8 * s2 + 3]), pack2(pv[8 * s2 + 4], pv[8 * s2 + 5]), pack2(pv[8 * s2 + 6], pv[8 * s2 + 7])};
;         const bf16x8 pf = __builtin_bit_cast(bf16x8, pk);
;         o0 = MFMA32(s2 == 0 ? vf00 : vf01, pf, o0); o1 = MFMA32(s2 == 0 ? vf10 : vf11, pf, o1);
.Lswaa_y1:
	s_cmp_eq_u32 s43, 0
	s_cbranch_scc1 .Lswaa_ypv
	s_lshl_b32 s4, s27, 6
	s_add_u32 s4, s4, 32
	v_add_u32_e32 v18, s4, v20
	v_med3_i32 v122, v18, s50, v19
	v_lshlrev_b32_e32 v122, 2, v122
	ds_read_b32 v122, v122 offset:49668
	v_add_u32_e32 v123, 1, v18
	v_med3_i32 v123, v123, s50, v19
	v_lshlrev_b32_e32 v123, 2, v123
	ds_read_b32 v123, v123 offset:49668
	v_add_u32_e32 v124, 2, v18
	v_med3_i32 v124, v124, s50, v19
	v_lshlrev_b32_e32 v124, 2, v124
	ds_read_b32 v124, v124 offset:49668
	v_add_u32_e32 v125, 3, v18
	v_med3_i32 v125, v125, s50, v19
	v_lshlrev_b32_e32 v125, 2, v125
	ds_read_b32 v125, v125 offset:49668
	v_add_u32_e32 v126, 8, v18
	v_med3_i32 v126, v126, s50, v19
	v_lshlrev_b32_e32 v126, 2, v126
	ds_read_b32 v126, v126 offset:49668
	v_add_u32_e32 v127, 9, v18
	v_med3_i32 v127, v127, s50, v19
	v_lshlrev_b32_e32 v127, 2, v127
	ds_read_b32 v127, v127 offset:49668
	v_add_u32_e32 v128, 10, v18
	v_med3_i32 v128, v128, s50, v19
	v_lshlrev_b32_e32 v128, 2, v128
	ds_read_b32 v128, v128 offset:49668
	v_add_u32_e32 v129, 11, v18
	v_med3_i32 v129, v129, s50, v19
	v_lshlrev_b32_e32 v129, 2, v129
	ds_read_b32 v129, v129 offset:49668
	v_add_u32_e32 v130, 16, v18
	v_med3_i32 v130, v130, s50, v19
	v_lshlrev_b32_e32 v130, 2, v130
	ds_read_b32 v130, v130 offset:49668
	v_add_u32_e32 v131, 17, v18
	v_med3_i32 v131, v131, s50, v19
	v_lshlrev_b32_e32 v131, 2, v131
	ds_read_b32 v131, v131 offset:49668
	v_add_u32_e32 v132, 18, v18
	v_med3_i32 v132, v132, s50, v19
	v_lshlrev_b32_e32 v132, 2, v132
	ds_read_b32 v132, v132 offset:49668
	v_add_u32_e32 v133, 19, v18
	v_med3_i32 v133, v133, s50, v19
	v_lshlrev_b32_e32 v133, 2, v133
	ds_read_b32 v133, v133 offset:49668
	v_add_u32_e32 v134, 24, v18
	v_med3_i32 v134, v134, s50, v19
	v_lshlrev_b32_e32 v134, 2, v134
	ds_read_b32 v134, v134 offset:49668
	v_add_u32_e32 v135, 25, v18
	v_med3_i32 v135, v135, s50, v19
	v_lshlrev_b32_e32 v135, 2, v135
	ds_read_b32 v135, v135 offset:49668
	v_add_u32_e32 v136, 26, v18
	v_med3_i32 v136, v136, s50, v19
	v_lshlrev_b32_e32 v136, 2, v136
	ds_read_b32 v136, v136 offset:49668
	v_add_u32_e32 v137, 27, v18
	v_med3_i32 v137, v137, s50, v19
	v_lshlrev_b32_e32 v137, 2, v137
	ds_read_b32 v137, v137 offset:49668
	s_waitcnt lgkmcnt(0)
	v_add_f32_e32 v74, v74, v122
	v_add_f32_e32 v75, v75, v123
	v_add_f32_e32 v76, v76, v124
	v_add_f32_e32 v77, v77, v125
	v_add_f32_e32 v78, v78, v126
	v_add_f32_e32 v79, v79, v127
	v_add_f32_e32 v80, v80, v128
	v_add_f32_e32 v81, v81, v129
	v_add_f32_e32 v82, v82, v130
	v_add_f32_e32 v83, v83, v131
	v_add_f32_e32 v84, v84, v132
	v_add_f32_e32 v85, v85, v133
	v_add_f32_e32 v86, v86, v134
	v_add_f32_e32 v87, v87, v135
	v_add_f32_e32 v88, v88, v136
	v_add_f32_e32 v89, v89, v137
	v_exp_f32_e32 v74, v74
	v_exp_f32_e32 v75, v75
	v_exp_f32_e32 v76, v76
	v_exp_f32_e32 v77, v77
	v_exp_f32_e32 v78, v78
	v_exp_f32_e32 v79, v79
	v_exp_f32_e32 v80, v80
	v_exp_f32_e32 v81, v81
	v_exp_f32_e32 v82, v82
	v_exp_f32_e32 v83, v83
	v_exp_f32_e32 v84, v84
	v_exp_f32_e32 v85, v85
	v_exp_f32_e32 v86, v86
	v_exp_f32_e32 v87, v87
	v_exp_f32_e32 v88, v88
	v_exp_f32_e32 v89, v89
	v_cvt_pk_bf16_f32 v178, v74, v75
	v_cvt_pk_bf16_f32 v179, v76, v77
	v_cvt_pk_bf16_f32 v180, v78, v79
	v_cvt_pk_bf16_f32 v181, v80, v81
	v_cvt_pk_bf16_f32 v182, v82, v83
	v_cvt_pk_bf16_f32 v183, v84, v85
	v_cvt_pk_bf16_f32 v184, v86, v87
	v_cvt_pk_bf16_f32 v185, v88, v89
	v_add_f32_e32 v192, v192, v74
	v_add_f32_e32 v193, v193, v75
	v_add_f32_e32 v192, v192, v76
	v_add_f32_e32 v193, v193, v77
	v_add_f32_e32 v192, v192, v78
	v_add_f32_e32 v193, v193, v79
	v_add_f32_e32 v192, v192, v80
	v_add_f32_e32 v193, v193, v81
	v_add_f32_e32 v192, v192, v82
	v_add_f32_e32 v193, v193, v83
	v_add_f32_e32 v192, v192, v84
	v_add_f32_e32 v193, v193, v85
	v_add_f32_e32 v192, v192, v86
	v_add_f32_e32 v193, v193, v87
	v_add_f32_e32 v192, v192, v88
	v_add_f32_e32 v193, v193, v89
.Lswaa_ypv:
	s_cmp_eq_u32 s42, 0
	s_cbranch_scc1 .Lswaa_pvskip0
	v_mfma_f32_32x32x16_bf16 v[26:41], v[138:141], v[170:173], v[26:41]
	v_mfma_f32_32x32x16_bf16 v[42:57], v[142:145], v[170:173], v[42:57]
	v_mfma_f32_32x32x16_bf16 v[26:41], v[146:149], v[174:177], v[26:41]
	v_mfma_f32_32x32x16_bf16 v[42:57], v[150:153], v[174:177], v[42:57]
; DI unsigned pack2(float lo, float hi) { f32x2 v = {lo, hi}; bf16v2 r = __builtin_convertvector(v, bf16v2); return __builtin_bit_cast(unsigned, r); }
; DI float shx(float v, int lane, int o) { return __int_as_float(__builtin_amdgcn_ds_bpermute((lane ^ o) << 2, __float_as_int(v))); }
; #define MFMA32(a, b, c) __builtin_amdgcn_mfma_f32_32x32x16_bf16((a), (b), (c), 0, 0, 0)
; template <int DQK, bool SWA, bool MASK, class KF, class VF>
; DI void attn_subtile(const bf16x8 (&qf)[DQK / 16], f32x16& o0, f32x16& o1, float& lsum, int kbase, int h, int qpos, int T, const LAS float* LUT, KF kfrag, VF vfrag) {
;     ...
; #pragma unroll
;     for (int s2 = 0; s2 < 2; ++s2) {
;         u32x4 pk = {pack2(pv[8 * s2], pv[8 * s2 + 1]), pack2(pv[8 * s2 + 2], pv[8 * s2 + 3]), pack2(pv[8 * s2 + 4], pv[8 * s2 + 5]), pack2(pv[8 * s2 + 6], pv[8 * s2 + 7])};
;         const bf16x8 pf = __builtin_bit_cast(bf16x8, pk);
;         o0 = MFMA32(s2 == 0 ? vf00 : vf01, pf, o0); o1 = MFMA32(s2 == 0 ? vf10 : vf11, pf, o1);
;     }
; template <int DQK, bool SWA>
; DI void attn_block(int wv, LAS unsigned char* lds, const bf16_t* Q, int ldq, int qoff, const bf16_t* K, int ldk, int koff, const bf16_t* Vt,
;                    int base, int T, int q0, bf16_t* O, int ldo, int ooff, const float* relb, int qhead, float sink_add) {
;     ...
;     for (int it = 0; it < ntl; it += 2) {
;         if (it + 1 < ntl) ATT_LWRITE(kB0, kB1, vB, 1);
;         if (it + 3 < ntl) ATT_GLOAD(kB0, kB1, vB, ATT_TILE(it + 3));
;         ATT_COMPUTE(it);
;         __syncthreads();
;         if (it + 1 < ntl) {
;             if (it + 2 < ntl) ATT_LWRITE(kA0, kA1, vA, 0);
;             if (it + 4 < ntl) ATT_GLOAD(kA0, kA1, vA, ATT_TILE(it + 4));
;             ATT_COMPUTE(it + 1);
;             __syncthreads();
;         }
;     }
;     ...
;     lsum += shx(lsum, lane, 32);
;     const float il = 1.f / (lsum + sink_add);
;     bf16_t* op = O + ((size_t)base + qpos) * ldo + ooff;
; #pragma unroll
;     for (int g4 = 0; g4 < 4; ++g4) {
;         u32x2 a = {pack2(o0[4 * g4] * il, o0[4 * g4 + 1] * il), pack2(o0[4 * g4 + 2] * il, o0[4 * g4 + 3] * il)};
;         u32x2 b = {pack2(o1[4 * g4] * il, o1[4 * g4 + 1] * il), pack2(o1[4 * g4 + 2] * il, o1[4 * g4 + 3] * il)};
;         *(u32x2*)(op + 8 * g4 + 4 * h) = a; *(u32x2*)(op + 32 + 8 * g4 + 4 * h) = b;
;     }
.Lswaa_pvskip0:
	s_cmp_eq_u32 s43, 0
	s_cbranch_scc1 .Lswaa_pvskip1
	v_mfma_f32_32x32x16_bf16 v[26:41], v[154:157], v[178:181], v[26:41]
	v_mfma_f32_32x32x16_bf16 v[42:57], v[158:161], v[178:181], v[42:57]
	v_mfma_f32_32x32x16_bf16 v[26:41], v[162:165], v[182:185], v[26:41]
	v_mfma_f32_32x32x16_bf16 v[42:57], v[166:169], v[182:185], v[42:57]
.Lswaa_pvskip1:
	s_barrier
	s_mov_b32 s31, s30
	s_add_u32 s30, s30, 0x4800
	s_cmp_eq_u32 s30, 0x9000
	s_cselect_b32 s30, 0xf000, s30
	s_cmp_eq_u32 s30, 0x1c800
	s_cselect_b32 s30, 0, s30
	s_add_u32 s14, s14, 1
	s_cmp_le_u32 s14, s29
	s_cbranch_scc1 .Lswaa_loop
	s_waitcnt vmcnt(0)
	s_cmpk_gt_u32 s15, 3
	s_cbranch_scc1 .Lswaa_noskew2
	s_barrier
.Lswaa_noskew2:
	s_nop 15
	v_add_f32_e32 v192, v192, v193
	v_xor_b32_e32 v197, 32, v254
	v_lshlrev_b32_e32 v197, 2, v197
	v_mov_b32_e32 v199, s46
	v_mul_f32_e32 v199, 0x3fb8aa3b, v199
	v_exp_f32_e32 v199, v199
	ds_bpermute_b32 v198, v197, v192
	s_waitcnt lgkmcnt(0)
	v_add_f32_e32 v192, v192, v198
	v_add_f32_e32 v192, v192, v199
	v_rcp_f32_e32 v192, v192
	s_nop 0
	v_mul_f32_e32 v26, v26, v192
	v_mul_f32_e32 v27, v27, v192
	v_mul_f32_e32 v28, v28, v192
	v_mul_f32_e32 v29, v29, v192
	v_mul_f32_e32 v30, v30, v192
	v_mul_f32_e32 v31, v31, v192
	v_mul_f32_e32 v32, v32, v192
	v_mul_f32_e32 v33, v33, v192
	v_mul_f32_e32 v34, v34, v192
	v_mul_f32_e32 v35, v35, v192
	v_mul_f32_e32 v36, v36, v192
	v_mul_f32_e32 v37, v37, v192
	v_mul_f32_e32 v38, v38, v192
	v_mul_f32_e32 v39, v39, v192
	v_mul_f32_e32 v40, v40, v192
	v_mul_f32_e32 v41, v41, v192
	v_mul_f32_e32 v42, v42, v192
	v_mul_f32_e32 v43, v43, v192
	v_mul_f32_e32 v44, v44, v192
	v_mul_f32_e32 v45, v45, v192
	v_mul_f32_e32 v46, v46, v192
	v_mul_f32_e32 v47, v47, v192
	v_mul_f32_e32 v48, v48, v192
	v_mul_f32_e32 v49, v49, v192
	v_mul_f32_e32 v50, v50, v192
	v_mul_f32_e32 v51, v51, v192
	v_mul_f32_e32 v52, v52, v192
	v_mul_f32_e32 v53, v53, v192
	v_mul_f32_e32 v54, v54, v192
	v_mul_f32_e32 v55, v55, v192
	v_mul_f32_e32 v56, v56, v192
	v_mul_f32_e32 v57, v57, v192
	v_cvt_pk_bf16_f32 v58, v26, v27
	v_cvt_pk_bf16_f32 v59, v28, v29
	v_cvt_pk_bf16_f32 v60, v42, v43
	v_cvt_pk_bf16_f32 v61, v44, v45
	v_cvt_pk_bf16_f32 v62, v30, v31
	v_cvt_pk_bf16_f32 v63, v32, v33
	v_cvt_pk_bf16_f32 v64, v46, v47
	v_cvt_pk_bf16_f32 v65, v48, v49
	v_cvt_pk_bf16_f32 v66, v34, v35
	v_cvt_pk_bf16_f32 v67, v36, v37
	v_cvt_pk_bf16_f32 v68, v50, v51
	v_cvt_pk_bf16_f32 v69, v52, v53
	v_cvt_pk_bf16_f32 v70, v38, v39
	v_cvt_pk_bf16_f32 v71, v40, v41
	v_cvt_pk_bf16_f32 v72, v54, v55
	v_cvt_pk_bf16_f32 v73, v56, v57
	global_store_dwordx2 v200, v[58:59], s[22:23] offset:0
	global_store_dwordx2 v200, v[60:61], s[22:23] offset:64
	global_store_dwordx2 v200, v[62:63], s[22:23] offset:16
	global_store_dwordx2 v200, v[64:65], s[22:23] offset:80
	global_store_dwordx2 v200, v[66:67], s[22:23] offset:32
	global_store_dwordx2 v200, v[68:69], s[22:23] offset:96
	global_store_dwordx2 v200, v[70:71], s[22:23] offset:48
	global_store_dwordx2 v200, v[72:73], s[22:23] offset:112
	v_readlane_b32 s4, v255, 17
	v_readlane_b32 s5, v255, 18
	v_readlane_b32 s6, v255, 19
	v_readlane_b32 s7, v255, 20
	v_readlane_b32 s8, v255, 21
	v_readlane_b32 s9, v255, 22
	v_readlane_b32 s10, v255, 23
	v_readlane_b32 s11, v255, 24
	v_readlane_b32 s12, v255, 25
	v_readlane_b32 s13, v255, 26
	v_readlane_b32 s14, v255, 27
	v_readlane_b32 s15, v255, 28
	v_readlane_b32 s16, v255, 29
	v_readlane_b32 s17, v255, 30
	v_readlane_b32 s18, v255, 31
	v_readlane_b32 s19, v255, 32
	v_readlane_b32 s20, v255, 33
	v_readlane_b32 s21, v255, 34
	v_readlane_b32 s22, v255, 35
	v_readlane_b32 s23, v255, 36
	v_readlane_b32 s24, v255, 37
	v_readlane_b32 s25, v255, 38
	v_readlane_b32 s26, v255, 39
	v_readlane_b32 s27, v255, 40
	v_readlane_b32 s28, v255, 41
	v_readlane_b32 s29, v255, 42
	v_readlane_b32 s30, v255, 43
	v_readlane_b32 s31, v255, 44
	v_readlane_b32 s36, v255, 45
	v_readlane_b32 s37, v255, 46
	v_readlane_b32 s38, v255, 47
	v_readlane_b32 s39, v255, 48
	v_readlane_b32 s40, v255, 49
	v_readlane_b32 s41, v255, 50
	v_readlane_b32 s42, v255, 51
	v_readlane_b32 s43, v255, 52
	v_readlane_b32 s44, v255, 53
	v_readlane_b32 s45, v255, 54
	v_readlane_b32 s46, v255, 55
	v_readlane_b32 s47, v255, 56
	v_readlane_b32 s48, v255, 57
	v_readlane_b32 s49, v255, 58
	v_readlane_b32 s50, v255, 59
	v_readlane_b32 s51, v255, 60
	s_nop 4
	s_branch .LBB0_1237

; #define LAS __attribute__((address_space(3)))
; DI unsigned pack2(float lo, float hi) { f32x2 v = {lo, hi}; bf16v2 r = __builtin_convertvector(v, bf16v2); return __builtin_bit_cast(unsigned, r); }
; DI float fexp2(float x) { return __builtin_amdgcn_exp2f(x); }
; #define MFMA32(a, b, c) __builtin_amdgcn_mfma_f32_32x32x16_bf16((a), (b), (c), 0, 0, 0)
; template <int DQK, bool MASK>
; DI void attn_tile64(const bf16x8 (&qf)[DQK / 16], f32x16& o0, f32x16& o1, float& lsum, int kbase0, int r, int h, int T, const LAS unsigned char* Ksm, const LAS unsigned char* Vsm) {
;     ...
;     bf16x8 pf[2][2];
;     f32x2 ls2 = {0.f, 0.f};
; #pragma unroll
;     for (int kt = 0; kt < 2; ++kt) {
;         float pv[16];
; #pragma unroll
;         for (int i = 0; i < 16; ++i) {
;             const float sv = sa[kt][i];
;             if (MASK) { const int kpos = kbase0 + 32 * kt + (i & 3) + 8 * (i >> 2) + 4 * h; const float e = fexp2(sv); pv[i] = kpos < T ? e : 0.f; } else pv[i] = fexp2(sv);
;         }
; #pragma unroll
;         for (int i = 0; i < 16; i += 2) ls2 = ls2 + (f32x2){pv[i], pv[i + 1]};
; #pragma unroll
;         for (int s2 = 0; s2 < 2; ++s2) {
;             u32x4 pk = {pack2(pv[8 * s2], pv[8 * s2 + 1]), pack2(pv[8 * s2 + 2], pv[8 * s2 + 3]), pack2(pv[8 * s2 + 4], pv[8 * s2 + 5]), pack2(pv[8 * s2 + 6], pv[8 * s2 + 7])};
;             pf[kt][s2] = __builtin_bit_cast(bf16x8, pk);
;         }
;     }
;     lsum += ls2[0] + ls2[1];
;     bf16x8 vf[2][2][2];
; #pragma unroll
;     for (int kt = 0; kt < 2; ++kt)
; #pragma unroll
;         for (int s2 = 0; s2 < 2; ++s2)
; #pragma unroll
;             for (int dt = 0; dt < 2; ++dt) {
;                 const u32x2 a0 = *(const LAS u32x2*)(Vsm + (32 * dt + r) * 144 + (32 * kt + 16 * s2 + 4 * h) * 2), a1 = *(const LAS u32x2*)(Vsm + (32 * dt + r) * 144 + (32 * kt + 16 * s2 + 8 + 4 * h) * 2);
;                 u32x4 av = {a0[0], a0[1], a1[0], a1[1]}; vf[kt][s2][dt] = __builtin_bit_cast(bf16x8, av);
;             }
; #pragma unroll
;     for (int kt = 0; kt < 2; ++kt)
; #pragma unroll
;         for (int s2 = 0; s2 < 2; ++s2) { o0 = MFMA32(vf[kt][s2][0], pf[kt][s2], o0); o1 = MFMA32(vf[kt][s2][1], pf[kt][s2], o1); }
.Lmlaa_noskew:
.Lmlaa_loop:
	v_add_u32_e32 v197, s30, v194
	v_add_u32_e32 v198, s30, v195
	v_add_u32_e32 v199, s30, v196
	ds_read_b128 v[90:93], v197 offset:0
	ds_read_b128 v[94:97], v197 offset:6656
	ds_read_b128 v[98:101], v197 offset:32
	ds_read_b128 v[102:105], v197 offset:6688
	ds_read_b128 v[106:109], v197 offset:64
	ds_read_b128 v[110:113], v197 offset:6720
	ds_read_b128 v[114:117], v197 offset:96
	ds_read_b128 v[118:121], v197 offset:6752
	ds_read_b128 v[122:125], v197 offset:128
	ds_read_b128 v[126:129], v197 offset:6784
	ds_read_b128 v[130:133], v197 offset:160
	ds_read_b128 v[134:137], v197 offset:6816
	s_waitcnt lgkmcnt(11)
	v_mfma_f32_32x32x16_bf16 v[58:73], v[90:93], v[2:5], 0
	ds_read_b64 v[138:139], v198 offset:0
	ds_read_b64 v[140:141], v198 offset:16
	s_waitcnt lgkmcnt(12)
	v_mfma_f32_32x32x16_bf16 v[74:89], v[94:97], v[2:5], 0
	ds_read_b64 v[142:143], v199 offset:0
	ds_read_b64 v[144:145], v199 offset:16
	s_waitcnt lgkmcnt(13)
	v_mfma_f32_32x32x16_bf16 v[58:73], v[98:101], v[6:9], v[58:73]
	ds_read_b64 v[146:147], v198 offset:32
	ds_read_b64 v[148:149], v198 offset:48
	s_waitcnt lgkmcnt(14)
	v_mfma_f32_32x32x16_bf16 v[74:89], v[102:105], v[6:9], v[74:89]
	ds_read_b64 v[150:151], v199 offset:32
	ds_read_b64 v[152:153], v199 offset:48
	s_waitcnt lgkmcnt(15)
	v_mfma_f32_32x32x16_bf16 v[58:73], v[106:109], v[10:13], v[58:73]
	ds_read_b64 v[154:155], v198 offset:64
	ds_read_b64 v[156:157], v198 offset:80
	s_waitcnt lgkmcnt(15)
	v_mfma_f32_32x32x16_bf16 v[74:89], v[110:113], v[10:13], v[74:89]
	ds_read_b64 v[158:159], v199 offset:64
	ds_read_b64 v[160:161], v199 offset:80
	s_waitcnt lgkmcnt(15)
	v_mfma_f32_32x32x16_bf16 v[58:73], v[114:117], v[14:17], v[58:73]
	ds_read_b64 v[162:163], v198 offset:96
	ds_read_b64 v[164:165], v198 offset:112
	s_waitcnt lgkmcnt(15)
	v_mfma_f32_32x32x16_bf16 v[74:89], v[118:121], v[14:17], v[74:89]
	ds_read_b64 v[166:167], v199 offset:96
	ds_read_b64 v[168:169], v199 offset:112
	s_waitcnt lgkmcnt(15)
	v_mfma_f32_32x32x16_bf16 v[58:73], v[122:125], v[18:21], v[58:73]
	s_waitcnt lgkmcnt(15)
	v_mfma_f32_32x32x16_bf16 v[74:89], v[126:129], v[18:21], v[74:89]
	s_waitcnt lgkmcnt(15)
	v_mfma_f32_32x32x16_bf16 v[58:73], v[130:133], v[22:25], v[58:73]
	s_waitcnt lgkmcnt(15)
	v_mfma_f32_32x32x16_bf16 v[74:89], v[134:137], v[22:25], v[74:89]
	s_waitcnt vmcnt(6) lgkmcnt(0)
	s_barrier
	s_add_u32 m0, s31, s24
	s_nop 0
	global_load_lds_dwordx4 v[186:187], off
	v_lshl_add_u64 v[186:187], v[186:187], 0, s[36:37]
	s_add_u32 m0, s31, s25
	s_nop 0
	global_load_lds_dwordx4 v[188:189], off
	v_lshl_add_u64 v[188:189], v[188:189], 0, s[38:39]
	s_add_u32 m0, s31, s26
	s_nop 0
	global_load_lds_dwordx4 v[190:191], off
	v_lshl_add_u64 v[190:191], v[190:191], 0, s[40:41]
	s_cmp_eq_u32 s14, s29
	s_cbranch_scc1 .Lmlaa_ylast
	s_nop 15
	v_exp_f32_e32 v58, v58
	v_exp_f32_e32 v59, v59
	v_exp_f32_e32 v60, v60
	v_exp_f32_e32 v61, v61
	v_exp_f32_e32 v62, v62
	v_exp_f32_e32 v63, v63
	v_exp_f32_e32 v64, v64
	v_exp_f32_e32 v65, v65
	v_exp_f32_e32 v66, v66
	v_exp_f32_e32 v67, v67
	v_exp_f32_e32 v68, v68
	v_exp_f32_e32 v69, v69
	v_exp_f32_e32 v70, v70
	v_exp_f32_e32 v71, v71
	v_exp_f32_e32 v72, v72
	v_exp_f32_e32 v73, v73
	v_cvt_pk_bf16_f32 v170, v58, v59
	v_cvt_pk_bf16_f32 v171, v60, v61
	v_cvt_pk_bf16_f32 v172, v62, v63
	v_cvt_pk_bf16_f32 v173, v64, v65
	v_cvt_pk_bf16_f32 v174, v66, v67
	v_cvt_pk_bf16_f32 v175, v68, v69
	v_cvt_pk_bf16_f32 v176, v70, v71
	v_cvt_pk_bf16_f32 v177, v72, v73
	v_exp_f32_e32 v74, v74
	v_exp_f32_e32 v75, v75
	v_exp_f32_e32 v76, v76
	v_exp_f32_e32 v77, v77
	v_exp_f32_e32 v78, v78
	v_exp_f32_e32 v79, v79
	v_exp_f32_e32 v80, v80
	v_exp_f32_e32 v81, v81
	v_exp_f32_e32 v82, v82
	v_exp_f32_e32 v83, v83
	v_exp_f32_e32 v84, v84
	v_exp_f32_e32 v85, v85
	v_exp_f32_e32 v86, v86
	v_exp_f32_e32 v87, v87
	v_exp_f32_e32 v88, v88
	v_exp_f32_e32 v89, v89
	v_cvt_pk_bf16_f32 v178, v74, v75
	v_cvt_pk_bf16_f32 v179, v76, v77
	v_cvt_pk_bf16_f32 v180, v78, v79
	v_cvt_pk_bf16_f32 v181, v80, v81
	v_cvt_pk_bf16_f32 v182, v82, v83
	v_cvt_pk_bf16_f32 v183, v84, v85
	v_cvt_pk_bf16_f32 v184, v86, v87
	v_cvt_pk_bf16_f32 v185, v88, v89
	v_add_f32_e32 v192, v192, v58
	v_add_f32_e32 v193, v193, v59
	v_add_f32_e32 v192, v192, v60
	v_add_f32_e32 v193, v193, v61
	v_add_f32_e32 v192, v192, v62
	v_add_f32_e32 v193, v193, v63
	v_add_f32_e32 v192, v192, v64
	v_add_f32_e32 v193, v193, v65
	v_add_f32_e32 v192, v192, v66
	v_add_f32_e32 v193, v193, v67
	v_add_f32_e32 v192, v192, v68
	v_add_f32_e32 v193, v193, v69
	v_add_f32_e32 v192, v192, v70
	v_add_f32_e32 v193, v193, v71
	v_add_f32_e32 v192, v192, v72
	v_add_f32_e32 v193, v193, v73
	v_add_f32_e32 v192, v192, v74
	v_add_f32_e32 v193, v193, v75
	v_add_f32_e32 v192, v192, v76
	v_add_f32_e32 v193, v193, v77
	v_add_f32_e32 v192, v192, v78
	v_add_f32_e32 v193, v193, v79
	v_add_f32_e32 v192, v192, v80
	v_add_f32_e32 v193, v193, v81
	v_add_f32_e32 v192, v192, v82
	v_add_f32_e32 v193, v193, v83
	v_add_f32_e32 v192, v192, v84
	v_add_f32_e32 v193, v193, v85
	v_add_f32_e32 v192, v192, v86
	v_add_f32_e32 v193, v193, v87
	v_add_f32_e32 v192, v192, v88
	v_add_f32_e32 v193, v193, v89
	v_mfma_f32_32x32x16_bf16 v[26:41], v[138:141], v[170:173], v[26:41]
	v_mfma_f32_32x32x16_bf16 v[42:57], v[142:145], v[170:173], v[42:57]
	v_mfma_f32_32x32x16_bf16 v[26:41], v[146:149], v[174:177], v[26:41]
	v_mfma_f32_32x32x16_bf16 v[42:57], v[150:153], v[174:177], v[42:57]
	v_mfma_f32_32x32x16_bf16 v[26:41], v[154:157], v[178:181], v[26:41]
	v_mfma_f32_32x32x16_bf16 v[42:57], v[158:161], v[178:181], v[42:57]
	v_mfma_f32_32x32x16_bf16 v[26:41], v[162:165], v[182:185], v[26:41]
	v_mfma_f32_32x32x16_bf16 v[42:57], v[166:169], v[182:185], v[42:57]
	s_branch .Lmlaa_yend
; #define LAS __attribute__((address_space(3)))
; DI unsigned pack2(float lo, float hi) { f32x2 v = {lo, hi}; bf16v2 r = __builtin_convertvector(v, bf16v2); return __builtin_bit_cast(unsigned, r); }
; DI float fexp2(float x) { return __builtin_amdgcn_exp2f(x); }
; #define MFMA32(a, b, c) __builtin_amdgcn_mfma_f32_32x32x16_bf16((a), (b), (c), 0, 0, 0)
; template <int DQK, bool MASK>
; DI void attn_tile64(const bf16x8 (&qf)[DQK / 16], f32x16& o0, f32x16& o1, float& lsum, int kbase0, int r, int h, int T, const LAS unsigned char* Ksm, const LAS unsigned char* Vsm) {
;     ...
;     bf16x8 pf[2][2];
;     f32x2 ls2 = {0.f, 0.f};
; #pragma unroll
;     for (int kt = 0; kt < 2; ++kt) {
;         float pv[16];
; #pragma unroll
;         for (int i = 0; i < 16; ++i) {
;             const float sv = sa[kt][i];
;             if (MASK) { const int kpos = kbase0 + 32 * kt + (i & 3) + 8 * (i >> 2) + 4 * h; const float e = fexp2(sv); pv[i] = kpos < T ? e : 0.f; } else pv[i] = fexp2(sv);
;         }
; #pragma unroll
;         for (int i = 0; i < 16; i += 2) ls2 = ls2 + (f32x2){pv[i], pv[i + 1]};
; #pragma unroll
;         for (int s2 = 0; s2 < 2; ++s2) {
;             u32x4 pk = {pack2(pv[8 * s2], pv[8 * s2 + 1]), pack2(pv[8 * s2 + 2], pv[8 * s2 + 3]), pack2(pv[8 * s2 + 4], pv[8 * s2 + 5]), pack2(pv[8 * s2 + 6], pv[8 * s2 + 7])};
;             pf[kt][s2] = __builtin_bit_cast(bf16x8, pk);
;         }
;     }
;     lsum += ls2[0] + ls2[1];
;     bf16x8 vf[2][2][2];
; #pragma unroll
;     for (int kt = 0; kt < 2; ++kt)
; #pragma unroll
;         for (int s2 = 0; s2 < 2; ++s2)
; #pragma unroll
;             for (int dt = 0; dt < 2; ++dt) {
;                 const u32x2 a0 = *(const LAS u32x2*)(Vsm + (32 * dt + r) * 144 + (32 * kt + 16 * s2 + 4 * h) * 2), a1 = *(const LAS u32x2*)(Vsm + (32 * dt + r) * 144 + (32 * kt + 16 * s2 + 8 + 4 * h) * 2);
;                 u32x4 av = {a0[0], a0[1], a1[0], a1[1]}; vf[kt][s2][dt] = __builtin_bit_cast(bf16x8, av);
;             }
; #pragma unroll
;     for (int kt = 0; kt < 2; ++kt)
; #pragma unroll
;         for (int s2 = 0; s2 < 2; ++s2) { o0 = MFMA32(vf[kt][s2][0], pf[kt][s2], o0); o1 = MFMA32(vf[kt][s2][1], pf[kt][s2], o1); }
.Lmlaa_ylast:
	s_nop 15
	v_exp_f32_e32 v58, v58
	v_exp_f32_e32 v59, v59
	v_exp_f32_e32 v60, v60
	v_exp_f32_e32 v61, v61
	v_exp_f32_e32 v62, v62
	v_exp_f32_e32 v63, v63
	v_exp_f32_e32 v64, v64
	v_exp_f32_e32 v65, v65
	v_mov_b32_e32 v66, 0
	v_mov_b32_e32 v67, 0
	v_mov_b32_e32 v68, 0
	v_mov_b32_e32 v69, 0
	v_mov_b32_e32 v70, 0
	v_mov_b32_e32 v71, 0
	v_mov_b32_e32 v72, 0
	v_mov_b32_e32 v73, 0
	v_cvt_pk_bf16_f32 v170, v58, v59
	v_cvt_pk_bf16_f32 v171, v60, v61
	v_cvt_pk_bf16_f32 v172, v62, v63
	v_cvt_pk_bf16_f32 v173, v64, v65
	v_cvt_pk_bf16_f32 v174, v66, v67
	v_cvt_pk_bf16_f32 v175, v68, v69
	v_cvt_pk_bf16_f32 v176, v70, v71
	v_cvt_pk_bf16_f32 v177, v72, v73
	v_mov_b32_e32 v74, 0
	v_mov_b32_e32 v75, 0
	v_mov_b32_e32 v76, 0
	v_mov_b32_e32 v77, 0
	v_mov_b32_e32 v78, 0
	v_mov_b32_e32 v79, 0
	v_mov_b32_e32 v80, 0
	v_mov_b32_e32 v81, 0
	v_mov_b32_e32 v82, 0
	v_mov_b32_e32 v83, 0
	v_mov_b32_e32 v84, 0
	v_mov_b32_e32 v85, 0
	v_mov_b32_e32 v86, 0
	v_mov_b32_e32 v87, 0
	v_mov_b32_e32 v88, 0
	v_mov_b32_e32 v89, 0
	s_nop 0
	v_cvt_pk_bf16_f32 v178, v74, v75
	v_cvt_pk_bf16_f32 v179, v76, v77
	v_cvt_pk_bf16_f32 v180, v78, v79
	v_cvt_pk_bf16_f32 v181, v80, v81
	v_cvt_pk_bf16_f32 v182, v82, v83
	v_cvt_pk_bf16_f32 v183, v84, v85
	v_cvt_pk_bf16_f32 v184, v86, v87
	v_cvt_pk_bf16_f32 v185, v88, v89
	v_add_f32_e32 v192, v192, v58
	v_add_f32_e32 v193, v193, v59
	v_add_f32_e32 v192, v192, v60
	v_add_f32_e32 v193, v193, v61
	v_add_f32_e32 v192, v192, v62
	v_add_f32_e32 v193, v193, v63
	v_add_f32_e32 v192, v192, v64
	v_add_f32_e32 v193, v193, v65
	v_add_f32_e32 v192, v192, v66
	v_add_f32_e32 v193, v193, v67
	v_add_f32_e32 v192, v192, v68
	v_add_f32_e32 v193, v193, v69
	v_add_f32_e32 v192, v192, v70
	v_add_f32_e32 v193, v193, v71
	v_add_f32_e32 v192, v192, v72
	v_add_f32_e32 v193, v193, v73
	v_add_f32_e32 v192, v192, v74
	v_add_f32_e32 v193, v193, v75
	v_add_f32_e32 v192, v192, v76
	v_add_f32_e32 v193, v193, v77
	v_add_f32_e32 v192, v192, v78
	v_add_f32_e32 v193, v193, v79
	v_add_f32_e32 v192, v192, v80
	v_add_f32_e32 v193, v193, v81
	v_add_f32_e32 v192, v192, v82
	v_add_f32_e32 v193, v193, v83
	v_add_f32_e32 v192, v192, v84
	v_add_f32_e32 v193, v193, v85
	v_add_f32_e32 v192, v192, v86
	v_add_f32_e32 v193, v193, v87
	v_add_f32_e32 v192, v192, v88
	v_add_f32_e32 v193, v193, v89
	v_mfma_f32_32x32x16_bf16 v[26:41], v[138:141], v[170:173], v[26:41]
	v_mfma_f32_32x32x16_bf16 v[42:57], v[142:145], v[170:173], v[42:57]
	v_mfma_f32_32x32x16_bf16 v[26:41], v[146:149], v[174:177], v[26:41]
	v_mfma_f32_32x32x16_bf16 v[42:57], v[150:153], v[174:177], v[42:57]
	v_mfma_f32_32x32x16_bf16 v[26:41], v[154:157], v[178:181], v[26:41]
	v_mfma_f32_32x32x16_bf16 v[42:57], v[158:161], v[178:181], v[42:57]
	v_mfma_f32_32x32x16_bf16 v[26:41], v[162:165], v[182:185], v[26:41]
	v_mfma_f32_32x32x16_bf16 v[42:57], v[166:169], v[182:185], v[42:57]

; DI float fexp2(float x) { return __builtin_amdgcn_exp2f(x); }
; DI void phase_queue(int wv, const Params& p, int l, LAS unsigned char* lds) {
;     ...
;     for (;;) {
;         __syncthreads();
;         if (tid_(wv) == 0) *bc = (int)atomicAdd(ctr, 1u);
;         __syncthreads();
;         int it = *bc;
;         if (it >= N_QITEMS) break;
;         if (it < N_CHAIN) { propagate_chain(wv, p, it, lds); continue; }
;         it -= N_CHAIN;
;         if (it < N_TAIL) {
;             const int seq = it / 12, hh = it % 12, T = seq_len(seq), q0 = T - 16;
;             if (hh < 4) attn_tail<96, false>(wv, lds, QM, 384, hh * 96, KM, 384, hh * 96, VTM + (size_t)hh * 64 * MPAD, seq_start(seq), T, q0, MIX, 1024, 768 + hh * 64, nullptr, 0, 0.f);
;             else { const int head = hh - 4; attn_tail<64, true>(wv, lds, QS, 512, head * 64, KS, 128, (head >> 2) * 64, VTS + (size_t)(head >> 2) * 64 * MPAD, seq_start(seq), T, q0, MIX, 1024, 256 + head * 64,
;                                                                p.in[3], head, fexp2(p.in[23][(size_t)l * 8 + head] * LOG2E)); }
;             continue;
;         }
;         it -= N_TAIL;
;         if (it < N_MLA) {
;             int seq, head, qb;
;             if (it < 256) { seq = 0; head = it & 3; qb = it >> 2; } else { const int m = it - 256; seq = 1 + (m >> 5); head = m & 3; qb = (m >> 2) & 7; }
;             attn_block<96, false>(wv, lds, QM, 384, head * 96, KM, 384, head * 96, VTM + (size_t)head * 64 * MPAD, seq_start(seq), seq_len(seq), qb * 256, MIX, 1024, 768 + head * 64, nullptr, 0, 0.f);
;             continue;
;         }
;         it -= N_MLA;
;         {
;             int seq, head, qb;
;             if (it < 512) { seq = 0; head = it & 7; qb = it >> 3; } else { const int m = it - 512; seq = 1 + (m >> 6); head = m & 7; qb = (m >> 3) & 7; }
;             attn_block<64, true>(wv, lds, QS, 512, head * 64, KS, 128, (head >> 2) * 64, VTS + (size_t)(head >> 2) * 64 * MPAD, seq_start(seq), seq_len(seq), qb * 256, MIX, 1024, 256 + head * 64,
.LBB0_2621:
	s_or_b64 exec, exec, s[4:5]
	s_waitcnt lgkmcnt(0)
	s_barrier
	ds_read_b32 v0, v1 offset:57344
	s_movk_i32 s4, 0x1193
	s_waitcnt lgkmcnt(0)
	v_cmp_lt_i32_e32 vcc, s4, v0
	v_readfirstlane_b32 s87, v0
	s_mov_b64 s[4:5], -1
	s_cbranch_vccnz .LBB0_2616
	s_cmpk_gt_i32 s87, 0x107
	s_cbranch_scc0 .LBB0_2872
	s_cmpk_gt_u32 s87, 0x293
	s_cbranch_scc0 .LBB0_2805
	s_cmpk_gt_u32 s87, 0x793
	s_cbranch_scc0 .LBB0_2759
	v_writelane_b32 v255, s4, 17
	v_writelane_b32 v255, s5, 18
	v_writelane_b32 v255, s6, 19
	v_writelane_b32 v255, s7, 20
	v_writelane_b32 v255, s8, 21
	v_writelane_b32 v255, s9, 22
	v_writelane_b32 v255, s10, 23
	v_writelane_b32 v255, s11, 24
	v_writelane_b32 v255, s12, 25
	v_writelane_b32 v255, s13, 26
	v_writelane_b32 v255, s14, 27
	v_writelane_b32 v255, s15, 28
	v_writelane_b32 v255, s16, 29
	v_writelane_b32 v255, s17, 30
	v_writelane_b32 v255, s18, 31
	v_writelane_b32 v255, s19, 32
	v_writelane_b32 v255, s20, 33
	v_writelane_b32 v255, s21, 34
	v_writelane_b32 v255, s22, 35
	v_writelane_b32 v255, s23, 36
	v_writelane_b32 v255, s24, 37
	v_writelane_b32 v255, s25, 38
	v_writelane_b32 v255, s26, 39
	v_writelane_b32 v255, s27, 40
	v_writelane_b32 v255, s28, 41
	v_writelane_b32 v255, s29, 42
	v_writelane_b32 v255, s30, 43
	v_writelane_b32 v255, s31, 44
	v_writelane_b32 v255, s36, 45
	v_writelane_b32 v255, s37, 46
	v_writelane_b32 v255, s38, 47
	v_writelane_b32 v255, s39, 48
	v_writelane_b32 v255, s40, 49
	v_writelane_b32 v255, s41, 50
	v_writelane_b32 v255, s42, 51
	v_writelane_b32 v255, s43, 52
	v_writelane_b32 v255, s44, 53
	v_writelane_b32 v255, s45, 54
	v_writelane_b32 v255, s46, 55
	v_writelane_b32 v255, s47, 56
	v_writelane_b32 v255, s48, 57
	v_writelane_b32 v255, s49, 58
	v_writelane_b32 v255, s50, 59
	v_writelane_b32 v255, s51, 60
	s_load_dwordx2 s[40:41], s[0:1], 0x120
	s_load_dwordx2 s[42:43], s[0:1], 0x18
	s_load_dwordx2 s[44:45], s[0:1], 0xb8
	s_sub_u32 s4, s87, 0x794
	s_cmpk_lt_u32 s4, 0x200
	s_cbranch_scc1 .Lswab_seq0
	s_sub_u32 s5, s4, 0x200
	s_lshr_b32 s9, s5, 6
	s_add_u32 s9, s9, 1
	s_and_b32 s8, s5, 7
	s_bfe_u32 s10, s5, 0x30003
	s_mul_i32 s11, s9, 0x810
	s_add_u32 s11, s11, 0x3800
	s_movk_i32 s13, 33
	s_branch .Lswab_dec

; #define LAS __attribute__((address_space(3)))
; DI float fexp2(float x) { return __builtin_amdgcn_exp2f(x); }
; DI void attn_lut(LAS float* LUT, int tid, const float* relb, int qhead) {
;     if (tid < 259) { const int rel = tid - 129, n = rel < 0 ? -rel : rel; int b;
;         if (n < 8) b = n; else { int m = (31 - __builtin_clz((unsigned)(n * n))) - 6; b = 8 + m; if (b > 15) b = 15; }
;         if (rel > 0) b += 16;
;         LUT[tid] = relb[b * 8 + qhead] * LOG2E; }
; }
; template <int DQK, bool SWA>
; DI void attn_block(int wv, LAS unsigned char* lds, const bf16_t* Q, int ldq, int qoff, const bf16_t* K, int ldk, int koff, const bf16_t* Vt,
;                    int base, int T, int q0, bf16_t* O, int ldo, int ooff, const float* relb, int qhead, float sink_add) {
;     constexpr int KP = DQK * 2 + 16, CPR = DQK / 8, NKC = 64 * CPR, NKS = DQK / 16, KSZ = 13312;
;     const int tid = tid_(wv), lane = tid & 63, w = tid >> 6, r = lane & 31, h = lane >> 5;
;     LAS float* LUT = (LAS float*)(lds + ATT_LUT);
;     __syncthreads();
;     if (SWA) attn_lut(LUT, tid, relb, qhead);
;     const int qw0 = q0 + 32 * w, qpos = qw0 + r; const size_t qrow = (size_t)base + qpos;
;     bf16x8 qf[NKS];
; #pragma unroll
;     for (int ks = 0; ks < NKS; ++ks) qf[ks] = *(const bf16x8*)(Q + qrow * ldq + qoff + 16 * ks + 8 * h);
;     f32x16 o0, o1;
; #pragma unroll
;     for (int i = 0; i < 16; ++i) { o0[i] = 0.f; o1[i] = 0.f; }
;     float lsum = 0.f;
;     const int nt = (T + 63) >> 6;
;     int lo = 0, ntl = nt;
;     if (SWA) { lo = (q0 - 128) >> 6; if (lo < 1) lo = 1; int hi = (q0 + 255 + 128) >> 6; if (hi > nt - 1) hi = nt - 1; ntl = 1 + (hi >= lo ? hi - lo + 1 : 0); }
;     u32x4 kA0, kA1, vA, kB0, kB1, vB;
;     kA1 = (u32x4){0u, 0u, 0u, 0u}; kB1 = kA1;
;     const int kc0 = tid, kc1 = tid + 512;
;     const int kkey0 = kc0 / CPR, kpart0 = kc0 % CPR, kkey1 = kc1 / CPR, kpart1 = kc1 % CPR;
;     const int vd = tid >> 3, vpart = tid & 7;
; DI void phase_queue(int wv, const Params& p, int l, LAS unsigned char* lds) {
;     ...
;             attn_block<64, true>(wv, lds, QS, 512, head * 64, KS, 128, (head >> 2) * 64, VTS + (size_t)(head >> 2) * 64 * MPAD, seq_start(seq), seq_len(seq), qb * 256, MIX, 1024, 256 + head * 64,
;                                  p.in[3], head, fexp2(p.in[23][(size_t)l * 8 + head] * LOG2E));
.Lswab_dec:
	s_lshr_b32 s15, s33, 6
	s_lshl_b32 s4, s10, 2
	s_sub_u32 s5, s4, 2
	s_cmp_eq_u32 s10, 0
	s_cselect_b32 s12, 1, s5
	s_add_u32 s5, s4, 5
	s_sub_u32 s6, s13, 1
	s_min_u32 s5, s5, s6
	s_sub_u32 s5, s5, s12
	s_add_u32 s29, s5, 1
	s_lshl_b32 s49, s10, 8
	s_lshl_b32 s4, s15, 5
	s_add_u32 s49, s49, s4
	s_movk_i32 s50, 0xff7f
	s_movk_i32 s51, 0xff80
	s_waitcnt lgkmcnt(0)
	s_lshl_b32 s4, s8, 2
	s_add_u32 s4, s4, 32
	s_load_dword s46, s[44:45], s4
	v_add_u32_e32 v21, s33, v254
	v_add_u32_e32 v25, 0xffffff7f, v21
	v_sub_u32_e32 v23, 0, v25
	v_max_i32_e32 v23, v25, v23
	v_mul_u32_u24_e32 v24, v23, v23
	v_ffbh_u32_e32 v24, v24
	v_sub_u32_e32 v24, 33, v24
	v_min_u32_e32 v24, 15, v24
	v_cmp_gt_u32_e32 vcc, 8, v23
	s_nop 1
	v_cndmask_b32_e32 v24, v24, v23, vcc
	v_cmp_lt_i32_e32 vcc, 0, v25
	s_nop 1
	v_cndmask_b32_e64 v23, 0, 16, vcc
	v_add_u32_e32 v24, v24, v23
	v_lshl_add_u32 v24, v24, 3, s8
	v_lshlrev_b32_e32 v24, 2, v24
	v_min_u32_e32 v24, 0x3fc, v24
	global_load_dword v24, v24, s[42:43]
	s_lshl_b32 s4, s8, 7
	s_add_u32 s16, s40, s4
	s_addc_u32 s17, s41, 0
	s_add_u32 s4, s4, 0x200
	s_add_u32 s22, s34, 0x19548000
	s_addc_u32 s23, s35, 0
	s_add_u32 s22, s22, s4
	s_addc_u32 s23, s23, 0
	s_lshr_b32 s5, s8, 2
	s_lshl_b32 s4, s5, 7
	s_lshl_b32 s6, s11, 8
	s_add_u32 s18, s40, 0x50c0000
	s_addc_u32 s19, s41, 0
	s_add_u32 s18, s18, s4
	s_addc_u32 s19, s19, 0
	s_add_u32 s18, s18, s6
	s_addc_u32 s19, s19, 0
	s_mul_i32 s4, s5, 0xa18000
	s_lshl_b32 s6, s11, 1
	s_add_u32 s20, s34, 0x300a8000
	s_addc_u32 s21, s35, 0
	s_add_u32 s20, s20, s4
	s_addc_u32 s21, s21, 0
	s_add_u32 s20, s20, s6
	s_addc_u32 s21, s21, 0
	v_and_b32_e32 v0, 31, v254
	v_lshrrev_b32_e32 v197, 5, v254
	v_mul_u32_u24_e32 v194, 0x90, v0
	v_add_u32_e32 v195, 0x2400, v194
	v_lshl_add_u32 v194, v197, 4, v194
	v_lshl_add_u32 v195, v197, 3, v195
	v_add_u32_e32 v196, 0x1200, v195
	v_add_u32_e32 v198, s49, v0
	v_lshlrev_b32_e32 v20, 2, v197
	v_sub_u32_e32 v20, v20, v198
	v_add_u32_e32 v198, s11, v198
	v_lshlrev_b32_e32 v199, 10, v198
	v_lshl_add_u32 v199, v197, 4, v199
	v_lshlrev_b32_e32 v198, 11, v198
	v_lshl_add_u32 v200, v197, 3, v198
	v_mov_b32_e32 v19, 0x81
	v_mov_b32_e32 v22, 0x80
	s_movk_i32 s48, 0x71c8
	s_mov_b32 s47, 0x28600
	s_movk_i32 s28, 0x80
	s_movk_i32 s27, 0x4000
	s_add_u32 s4, s15, 0
	s_cmpk_gt_u32 s4, 8
	s_cselect_b32 s7, s47, 0x100
	s_cselect_b32 s36, s28, s27
	s_mov_b32 s37, 0
	s_cselect_b32 s42, s20, s18
	s_cselect_b32 s43, s21, s19
	s_cselect_b32 s5, 9, 0
	s_cselect_b32 s6, 0x2400, 0
	s_sub_u32 s4, s4, s5
	s_cmpk_gt_u32 s4, 8
	s_cselect_b32 s5, 9, 0
	s_sub_u32 s4, s4, s5
	s_lshl_b32 s5, s4, 10
	s_add_u32 s24, s5, s6
	s_lshl_b32 s4, s4, 6
	v_add_u32_e32 v197, s4, v254
	v_mul_lo_u32 v198, v197, s48
	v_lshrrev_b32_e32 v198, 18, v198
	v_mul_u32_u24_e32 v186, 9, v198
	v_sub_u32_e32 v197, v197, v186
	v_cmp_ne_u32_e32 vcc, 8, v197
	s_nop 1
	v_cndmask_b32_e32 v197, 0, v197, vcc
	v_mul_lo_u32 v198, v198, s7
	v_lshl_add_u32 v186, v197, 4, v198
	v_mov_b32_e32 v187, 0
	v_lshl_add_u64 v[186:187], s[42:43], 0, v[186:187]
	s_add_u32 s4, s15, 8
	s_cmpk_gt_u32 s4, 8
	s_cselect_b32 s7, s47, 0x100
	s_cselect_b32 s38, s28, s27
	s_mov_b32 s39, 0
	s_cselect_b32 s42, s20, s18
	s_cselect_b32 s43, s21, s19
	s_cselect_b32 s5, 9, 0
	s_cselect_b32 s6, 0x2400, 0
	s_sub_u32 s4, s4, s5
	s_cmpk_gt_u32 s4, 8
	s_cselect_b32 s5, 9, 0
	s_sub_u32 s4, s4, s5
	s_lshl_b32 s5, s4, 10
	s_add_u32 s25, s5, s6
	s_lshl_b32 s4, s4, 6
	v_add_u32_e32 v197, s4, v254
	v_mul_lo_u32 v198, v197, s48
	v_lshrrev_b32_e32 v198, 18, v198
	v_mul_u32_u24_e32 v188, 9, v198
	v_sub_u32_e32 v197, v197, v188
	v_cmp_ne_u32_e32 vcc, 8, v197
	s_nop 1
	v_cndmask_b32_e32 v197, 0, v197, vcc
	v_mul_lo_u32 v198, v198, s7
	v_lshl_add_u32 v188, v197, 4, v198
	v_mov_b32_e32 v189, 0
	v_lshl_add_u64 v[188:189], s[42:43], 0, v[188:189]
	s_add_u32 s4, s15, 16
	s_cmpk_gt_u32 s4, 8
	s_cselect_b32 s7, s47, 0x100
	s_cselect_b32 s40, s28, s27
	s_mov_b32 s41, 0
; #define ATT_GLOAD(k0_, k1_, v_, tile) do { const size_t rb = (size_t)base + (size_t)(tile) * 64; \
;         k0_ = *(const u32x4*)(K + (rb + kkey0) * ldk + koff + kpart0 * 8); \
;         if (kc1 < NKC) k1_ = *(const u32x4*)(K + (rb + kkey1) * ldk + koff + kpart1 * 8); \
;         v_ = *(const u32x4*)(Vt + (size_t)vd * MPAD + rb + vpart * 8); } while (0)
; #define ATT_LWRITE(k0_, k1_, v_, b) do { LAS unsigned char* kb = lds + (b) * ATT_BUF; \
;         *(LAS u32x4*)(kb + kkey0 * KP + kpart0 * 16) = k0_; \
;         if (kc1 < NKC) *(LAS u32x4*)(kb + kkey1 * KP + kpart1 * 16) = k1_; \
;         *(LAS u32x4*)(kb + KSZ + vd * 144 + vpart * 16) = v_; } while (0)
; template <int DQK, bool SWA>
; DI void attn_block(int wv, LAS unsigned char* lds, const bf16_t* Q, int ldq, int qoff, const bf16_t* K, int ldk, int koff, const bf16_t* Vt,
;                    int base, int T, int q0, bf16_t* O, int ldo, int ooff, const float* relb, int qhead, float sink_add) {
;     ...
;     u32x4 kA0, kA1, vA, kB0, kB1, vB;
;     kA1 = (u32x4){0u, 0u, 0u, 0u}; kB1 = kA1;
;     const int kc0 = tid, kc1 = tid + 512;
;     const int kkey0 = kc0 / CPR, kpart0 = kc0 % CPR, kkey1 = kc1 / CPR, kpart1 = kc1 % CPR;
;     const int vd = tid >> 3, vpart = tid & 7;
;     ...
;     ATT_GLOAD(kA0, kA1, vA, ATT_TILE(0)); ATT_LWRITE(kA0, kA1, vA, 0);
;     if (ntl > 1) ATT_GLOAD(kB0, kB1, vB, ATT_TILE(1));
;     if (ntl > 2) ATT_GLOAD(kA0, kA1, vA, ATT_TILE(2));
;     __syncthreads();
	s_cselect_b32 s42, s20, s18
	s_cselect_b32 s43, s21, s19
	s_cselect_b32 s5, 9, 0
	s_cselect_b32 s6, 0x2400, 0
	s_sub_u32 s4, s4, s5
	s_cmpk_gt_u32 s4, 8
	s_cselect_b32 s5, 9, 0
	s_sub_u32 s4, s4, s5
	s_lshl_b32 s5, s4, 10
	s_add_u32 s26, s5, s6
	s_lshl_b32 s4, s4, 6
	v_add_u32_e32 v197, s4, v254
	v_mul_lo_u32 v198, v197, s48
	v_lshrrev_b32_e32 v198, 18, v198
	v_mul_u32_u24_e32 v190, 9, v198
	v_sub_u32_e32 v197, v197, v190
	v_cmp_ne_u32_e32 vcc, 8, v197
	s_nop 1
	v_cndmask_b32_e32 v197, 0, v197, vcc
	v_mul_lo_u32 v198, v198, s7
	v_lshl_add_u32 v190, v197, 4, v198
	v_mov_b32_e32 v191, 0
	v_lshl_add_u64 v[190:191], s[42:43], 0, v[190:191]
	global_load_dwordx4 v[2:5], v199, s[16:17] offset:0
	global_load_dwordx4 v[6:9], v199, s[16:17] offset:32
	global_load_dwordx4 v[10:13], v199, s[16:17] offset:64
	global_load_dwordx4 v[14:17], v199, s[16:17] offset:96
	s_mov_b32 s28, 0x0
	s_add_u32 m0, s28, s24
	s_nop 0
	global_load_lds_dwordx4 v[186:187], off
	s_mul_i32 s4, s36, s12
	s_mov_b32 s5, 0
	v_lshl_add_u64 v[186:187], v[186:187], 0, s[4:5]
	s_add_u32 m0, s28, s25
	s_nop 0
	global_load_lds_dwordx4 v[188:189], off
	s_mul_i32 s4, s38, s12
	s_mov_b32 s5, 0
	v_lshl_add_u64 v[188:189], v[188:189], 0, s[4:5]
	s_add_u32 m0, s28, s26
	s_nop 0
	global_load_lds_dwordx4 v[190:191], off
	s_mul_i32 s4, s40, s12
	s_mov_b32 s5, 0
	v_lshl_add_u64 v[190:191], v[190:191], 0, s[4:5]
	s_mov_b32 s28, 0x4800
	s_add_u32 m0, s28, s24
	s_nop 0
	global_load_lds_dwordx4 v[186:187], off
	v_lshl_add_u64 v[186:187], v[186:187], 0, s[36:37]
	s_add_u32 m0, s28, s25
	s_nop 0
	global_load_lds_dwordx4 v[188:189], off
	v_lshl_add_u64 v[188:189], v[188:189], 0, s[38:39]
	s_add_u32 m0, s28, s26
	s_nop 0
	global_load_lds_dwordx4 v[190:191], off
	v_lshl_add_u64 v[190:191], v[190:191], 0, s[40:41]
	s_mov_b32 s28, 0xf000
	s_add_u32 m0, s28, s24
	s_nop 0
	global_load_lds_dwordx4 v[186:187], off
	v_lshl_add_u64 v[186:187], v[186:187], 0, s[36:37]
	s_add_u32 m0, s28, s25
	s_nop 0
	global_load_lds_dwordx4 v[188:189], off
	v_lshl_add_u64 v[188:189], v[188:189], 0, s[38:39]
	s_add_u32 m0, s28, s26
	s_nop 0
	global_load_lds_dwordx4 v[190:191], off
	v_lshl_add_u64 v[190:191], v[190:191], 0, s[40:41]
	s_mov_b32 s28, 0x13800
	s_add_u32 m0, s28, s24
	s_nop 0
	global_load_lds_dwordx4 v[186:187], off
	v_lshl_add_u64 v[186:187], v[186:187], 0, s[36:37]
	s_add_u32 m0, s28, s25
	s_nop 0
	global_load_lds_dwordx4 v[188:189], off
	v_lshl_add_u64 v[188:189], v[188:189], 0, s[38:39]
	s_add_u32 m0, s28, s26
	s_nop 0
	global_load_lds_dwordx4 v[190:191], off
	v_lshl_add_u64 v[190:191], v[190:191], 0, s[40:41]
	v_mov_b32_e32 v26, 0
	v_mov_b32_e32 v27, 0
	v_mov_b32_e32 v28, 0
	v_mov_b32_e32 v29, 0
	v_mov_b32_e32 v30, 0
	v_mov_b32_e32 v31, 0
	v_mov_b32_e32 v32, 0
	v_mov_b32_e32 v33, 0
	v_mov_b32_e32 v34, 0
	v_mov_b32_e32 v35, 0
	v_mov_b32_e32 v36, 0
	v_mov_b32_e32 v37, 0
	v_mov_b32_e32 v38, 0
	v_mov_b32_e32 v39, 0
	v_mov_b32_e32 v40, 0
	v_mov_b32_e32 v41, 0
	v_mov_b32_e32 v42, 0
	v_mov_b32_e32 v43, 0
	v_mov_b32_e32 v44, 0
	v_mov_b32_e32 v45, 0
	v_mov_b32_e32 v46, 0
	v_mov_b32_e32 v47, 0
	v_mov_b32_e32 v48, 0
	v_mov_b32_e32 v49, 0
	v_mov_b32_e32 v50, 0
	v_mov_b32_e32 v51, 0
	v_mov_b32_e32 v52, 0
	v_mov_b32_e32 v53, 0
	v_mov_b32_e32 v54, 0
	v_mov_b32_e32 v55, 0
	v_mov_b32_e32 v56, 0
	v_mov_b32_e32 v57, 0
	v_mov_b32_e32 v192, 0
	v_mov_b32_e32 v193, 0
	s_waitcnt vmcnt(16)
	v_mul_f32_e32 v24, 0x3fb8aa3b, v24
	v_mov_b32_e32 v23, 0xf149f2ca
	v_cmp_eq_u32_e32 vcc, 0, v21
	s_nop 1
	v_cndmask_b32_e32 v24, v24, v23, vcc
	v_cmp_eq_u32_e32 vcc, 0x102, v21
	s_nop 1
	v_cndmask_b32_e32 v24, v24, v23, vcc
	v_lshlrev_b32_e32 v25, 2, v21
	v_cmp_gt_u32_e32 vcc, 0x103, v21
	s_and_saveexec_b64 s[4:5], vcc
	ds_write_b32 v25, v24 offset:49152
	s_mov_b64 exec, s[4:5]
	s_mov_b32 s14, 0
	s_mov_b32 s30, 0x0
	s_mov_b32 s31, 0x18000
	s_waitcnt vmcnt(9) lgkmcnt(0)
	s_barrier
	s_cmpk_lt_u32 s15, 4
	s_cbranch_scc1 .Lswab_noskew
	s_barrier
